# scan waves: k^d four steps ahead, a wait every step that leaves the last two steps' LDS reads outstanding (two steps of latency slack)
# speedup vs baseline: 1.0044x; 1.0005x over previous
.Lsc_S_loop:
	v_pk_fma_f32 v[10:11], v[80:81], v[30:31], v[16:17] op_sel_hi:[1,0,1] neg_lo:[0,1,0] neg_hi:[0,1,0]
	v_pk_fma_f32 v[8:9], v[82:83], v[30:31], v[18:19] op_sel_hi:[1,0,1] neg_lo:[0,1,0] neg_hi:[0,1,0]
	v_pk_mul_f32 v[24:25], v[10:11], v[84:85] op_sel:[0,0] op_sel_hi:[0,1]
	v_pk_fma_f32 v[24:25], v[10:11], v[86:87], v[24:25] op_sel:[1,0,0] op_sel_hi:[1,1,1]
	v_pk_fma_f32 v[24:25], v[8:9], v[88:89], v[24:25] op_sel:[0,0,0] op_sel_hi:[0,1,1]
	v_pk_fma_f32 v[24:25], v[8:9], v[90:91], v[24:25] op_sel:[1,0,0] op_sel_hi:[1,1,1]
	v_pk_fma_f32 v[16:17], v[92:93], v[156:157], v[10:11] op_sel:[0,1,0] op_sel_hi:[1,1,1]
	v_pk_fma_f32 v[18:19], v[94:95], v[156:157], v[8:9] op_sel:[0,1,0] op_sel_hi:[1,1,1]
	v_add_f32_dpp v15, v24, v24 row_ror:8 row_mask:0xf bank_mask:0xf bound_ctrl:1
	ds_read_b128 v[76:79], v34 offset:4096
	s_nop 0
	v_add_f32_dpp v15, v15, v15 row_ror:4 row_mask:0xf bank_mask:0xf bound_ctrl:1
	ds_read_b128 v[128:131], v34 offset:3328
	ds_read_b128 v[132:135], v34 offset:3584
	v_add_f32_dpp v15, v15, v15 row_ror:2 row_mask:0xf bank_mask:0xf bound_ctrl:1
	ds_read_b128 v[136:139], v34 offset:3840
	ds_read_b128 v[160:163], v35 offset:16
	v_add_f32_dpp v30, v15, v15 row_ror:1 row_mask:0xf bank_mask:0xf bound_ctrl:1
	s_waitcnt lgkmcnt(11)
	v_pk_fma_f32 v[10:11], v[96:97], v[30:31], v[16:17] op_sel_hi:[1,0,1] neg_lo:[0,1,0] neg_hi:[0,1,0]
	v_pk_fma_f32 v[8:9], v[98:99], v[30:31], v[18:19] op_sel_hi:[1,0,1] neg_lo:[0,1,0] neg_hi:[0,1,0]
	v_pk_mul_f32 v[26:27], v[10:11], v[100:101] op_sel:[0,0] op_sel_hi:[0,1]
	v_pk_fma_f32 v[26:27], v[10:11], v[102:103], v[26:27] op_sel:[1,0,0] op_sel_hi:[1,1,1]
	v_pk_fma_f32 v[26:27], v[8:9], v[104:105], v[26:27] op_sel:[0,0,0] op_sel_hi:[0,1,1]
	v_pk_fma_f32 v[26:27], v[8:9], v[106:107], v[26:27] op_sel:[1,0,0] op_sel_hi:[1,1,1]
	v_pk_fma_f32 v[16:17], v[108:109], v[158:159], v[10:11] op_sel_hi:[1,0,1]
	v_pk_fma_f32 v[18:19], v[110:111], v[158:159], v[8:9] op_sel_hi:[1,0,1]
	v_add_f32_dpp v15, v26, v26 row_ror:8 row_mask:0xf bank_mask:0xf bound_ctrl:1
	ds_read_b128 v[92:95], v34 offset:5120
	s_nop 0
	v_add_f32_dpp v15, v15, v15 row_ror:4 row_mask:0xf bank_mask:0xf bound_ctrl:1
	ds_read_b128 v[80:83], v34 offset:4352
	ds_read_b128 v[84:87], v34 offset:4608
	v_add_f32_dpp v15, v15, v15 row_ror:2 row_mask:0xf bank_mask:0xf bound_ctrl:1
	ds_read_b128 v[88:91], v34 offset:4864
	ds_write2st64_b32 v37, v25, v27 offset0:0 offset1:4
	v_add_f32_dpp v30, v15, v15 row_ror:1 row_mask:0xf bank_mask:0xf bound_ctrl:1
	s_waitcnt lgkmcnt(10)
	v_pk_fma_f32 v[10:11], v[112:113], v[30:31], v[16:17] op_sel_hi:[1,0,1] neg_lo:[0,1,0] neg_hi:[0,1,0]
	v_pk_fma_f32 v[8:9], v[114:115], v[30:31], v[18:19] op_sel_hi:[1,0,1] neg_lo:[0,1,0] neg_hi:[0,1,0]
	v_pk_mul_f32 v[24:25], v[10:11], v[116:117] op_sel:[0,0] op_sel_hi:[0,1]
	v_pk_fma_f32 v[24:25], v[10:11], v[118:119], v[24:25] op_sel:[1,0,0] op_sel_hi:[1,1,1]
	v_pk_fma_f32 v[24:25], v[8:9], v[120:121], v[24:25] op_sel:[0,0,0] op_sel_hi:[0,1,1]
	v_pk_fma_f32 v[24:25], v[8:9], v[122:123], v[24:25] op_sel:[1,0,0] op_sel_hi:[1,1,1]
	v_pk_fma_f32 v[16:17], v[124:125], v[158:159], v[10:11] op_sel:[0,1,0] op_sel_hi:[1,1,1]
	v_pk_fma_f32 v[18:19], v[126:127], v[158:159], v[8:9] op_sel:[0,1,0] op_sel_hi:[1,1,1]
	v_add_f32_dpp v15, v24, v24 row_ror:8 row_mask:0xf bank_mask:0xf bound_ctrl:1
	ds_read_b128 v[108:111], v34 offset:6144
	s_nop 0
	v_add_f32_dpp v15, v15, v15 row_ror:4 row_mask:0xf bank_mask:0xf bound_ctrl:1
	ds_read_b128 v[96:99], v34 offset:5376
	ds_read_b128 v[100:103], v34 offset:5632
	v_add_f32_dpp v15, v15, v15 row_ror:2 row_mask:0xf bank_mask:0xf bound_ctrl:1
	ds_read_b128 v[104:107], v34 offset:5888
	s_nop 0
	v_add_f32_dpp v30, v15, v15 row_ror:1 row_mask:0xf bank_mask:0xf bound_ctrl:1
	s_waitcnt lgkmcnt(9)
	v_pk_fma_f32 v[10:11], v[128:129], v[30:31], v[16:17] op_sel_hi:[1,0,1] neg_lo:[0,1,0] neg_hi:[0,1,0]
	v_pk_fma_f32 v[8:9], v[130:131], v[30:31], v[18:19] op_sel_hi:[1,0,1] neg_lo:[0,1,0] neg_hi:[0,1,0]
	v_pk_mul_f32 v[26:27], v[10:11], v[132:133] op_sel:[0,0] op_sel_hi:[0,1]
	v_pk_fma_f32 v[26:27], v[10:11], v[134:135], v[26:27] op_sel:[1,0,0] op_sel_hi:[1,1,1]
	v_pk_fma_f32 v[26:27], v[8:9], v[136:137], v[26:27] op_sel:[0,0,0] op_sel_hi:[0,1,1]
	v_pk_fma_f32 v[26:27], v[8:9], v[138:139], v[26:27] op_sel:[1,0,0] op_sel_hi:[1,1,1]
	v_pk_fma_f32 v[16:17], v[76:77], v[160:161], v[10:11] op_sel_hi:[1,0,1]
	v_pk_fma_f32 v[18:19], v[78:79], v[160:161], v[8:9] op_sel_hi:[1,0,1]
	v_add_f32_dpp v15, v26, v26 row_ror:8 row_mask:0xf bank_mask:0xf bound_ctrl:1
	ds_read_b128 v[124:127], v34 offset:7168
	s_nop 0
	v_add_f32_dpp v15, v15, v15 row_ror:4 row_mask:0xf bank_mask:0xf bound_ctrl:1
	ds_read_b128 v[112:115], v34 offset:6400
	ds_read_b128 v[116:119], v34 offset:6656
	v_add_f32_dpp v15, v15, v15 row_ror:2 row_mask:0xf bank_mask:0xf bound_ctrl:1
	ds_read_b128 v[120:123], v34 offset:6912
	ds_write2st64_b32 v37, v25, v27 offset0:8 offset1:12
	v_add_f32_dpp v30, v15, v15 row_ror:1 row_mask:0xf bank_mask:0xf bound_ctrl:1
	s_waitcnt lgkmcnt(9)
	v_pk_fma_f32 v[10:11], v[80:81], v[30:31], v[16:17] op_sel_hi:[1,0,1] neg_lo:[0,1,0] neg_hi:[0,1,0]
	v_pk_fma_f32 v[8:9], v[82:83], v[30:31], v[18:19] op_sel_hi:[1,0,1] neg_lo:[0,1,0] neg_hi:[0,1,0]
	v_pk_mul_f32 v[24:25], v[10:11], v[84:85] op_sel:[0,0] op_sel_hi:[0,1]
	v_pk_fma_f32 v[24:25], v[10:11], v[86:87], v[24:25] op_sel:[1,0,0] op_sel_hi:[1,1,1]
	v_pk_fma_f32 v[24:25], v[8:9], v[88:89], v[24:25] op_sel:[0,0,0] op_sel_hi:[0,1,1]
	v_pk_fma_f32 v[24:25], v[8:9], v[90:91], v[24:25] op_sel:[1,0,0] op_sel_hi:[1,1,1]
	v_pk_fma_f32 v[16:17], v[92:93], v[160:161], v[10:11] op_sel:[0,1,0] op_sel_hi:[1,1,1]
	v_pk_fma_f32 v[18:19], v[94:95], v[160:161], v[8:9] op_sel:[0,1,0] op_sel_hi:[1,1,1]
	v_add_f32_dpp v15, v24, v24 row_ror:8 row_mask:0xf bank_mask:0xf bound_ctrl:1
	ds_read_b128 v[76:79], v34 offset:8192
	s_nop 0
	v_add_f32_dpp v15, v15, v15 row_ror:4 row_mask:0xf bank_mask:0xf bound_ctrl:1
	ds_read_b128 v[128:131], v34 offset:7424
	ds_read_b128 v[132:135], v34 offset:7680
	v_add_f32_dpp v15, v15, v15 row_ror:2 row_mask:0xf bank_mask:0xf bound_ctrl:1
	ds_read_b128 v[136:139], v34 offset:7936
	ds_read_b128 v[156:159], v35 offset:32
	v_add_f32_dpp v30, v15, v15 row_ror:1 row_mask:0xf bank_mask:0xf bound_ctrl:1
	s_waitcnt lgkmcnt(10)
	v_pk_fma_f32 v[10:11], v[96:97], v[30:31], v[16:17] op_sel_hi:[1,0,1] neg_lo:[0,1,0] neg_hi:[0,1,0]
	v_pk_fma_f32 v[8:9], v[98:99], v[30:31], v[18:19] op_sel_hi:[1,0,1] neg_lo:[0,1,0] neg_hi:[0,1,0]
	v_pk_mul_f32 v[26:27], v[10:11], v[100:101] op_sel:[0,0] op_sel_hi:[0,1]
	v_pk_fma_f32 v[26:27], v[10:11], v[102:103], v[26:27] op_sel:[1,0,0] op_sel_hi:[1,1,1]
	v_pk_fma_f32 v[26:27], v[8:9], v[104:105], v[26:27] op_sel:[0,0,0] op_sel_hi:[0,1,1]
	v_pk_fma_f32 v[26:27], v[8:9], v[106:107], v[26:27] op_sel:[1,0,0] op_sel_hi:[1,1,1]
	v_pk_fma_f32 v[16:17], v[108:109], v[162:163], v[10:11] op_sel_hi:[1,0,1]
	v_pk_fma_f32 v[18:19], v[110:111], v[162:163], v[8:9] op_sel_hi:[1,0,1]
	v_add_f32_dpp v15, v26, v26 row_ror:8 row_mask:0xf bank_mask:0xf bound_ctrl:1
	ds_read_b128 v[92:95], v34 offset:9216
	s_nop 0
	v_add_f32_dpp v15, v15, v15 row_ror:4 row_mask:0xf bank_mask:0xf bound_ctrl:1
	ds_read_b128 v[80:83], v34 offset:8448
	ds_read_b128 v[84:87], v34 offset:8704
	v_add_f32_dpp v15, v15, v15 row_ror:2 row_mask:0xf bank_mask:0xf bound_ctrl:1
	ds_read_b128 v[88:91], v34 offset:8960
	ds_write2st64_b32 v37, v25, v27 offset0:16 offset1:20
	v_add_f32_dpp v30, v15, v15 row_ror:1 row_mask:0xf bank_mask:0xf bound_ctrl:1
	s_waitcnt lgkmcnt(10)
	v_pk_fma_f32 v[10:11], v[112:113], v[30:31], v[16:17] op_sel_hi:[1,0,1] neg_lo:[0,1,0] neg_hi:[0,1,0]
	v_pk_fma_f32 v[8:9], v[114:115], v[30:31], v[18:19] op_sel_hi:[1,0,1] neg_lo:[0,1,0] neg_hi:[0,1,0]
	v_pk_mul_f32 v[24:25], v[10:11], v[116:117] op_sel:[0,0] op_sel_hi:[0,1]
	v_pk_fma_f32 v[24:25], v[10:11], v[118:119], v[24:25] op_sel:[1,0,0] op_sel_hi:[1,1,1]
	v_pk_fma_f32 v[24:25], v[8:9], v[120:121], v[24:25] op_sel:[0,0,0] op_sel_hi:[0,1,1]
	v_pk_fma_f32 v[24:25], v[8:9], v[122:123], v[24:25] op_sel:[1,0,0] op_sel_hi:[1,1,1]
	v_pk_fma_f32 v[16:17], v[124:125], v[162:163], v[10:11] op_sel:[0,1,0] op_sel_hi:[1,1,1]
	v_pk_fma_f32 v[18:19], v[126:127], v[162:163], v[8:9] op_sel:[0,1,0] op_sel_hi:[1,1,1]
	v_add_f32_dpp v15, v24, v24 row_ror:8 row_mask:0xf bank_mask:0xf bound_ctrl:1
	ds_read_b128 v[108:111], v34 offset:10240
	s_nop 0
	v_add_f32_dpp v15, v15, v15 row_ror:4 row_mask:0xf bank_mask:0xf bound_ctrl:1
	ds_read_b128 v[96:99], v34 offset:9472
	ds_read_b128 v[100:103], v34 offset:9728
	v_add_f32_dpp v15, v15, v15 row_ror:2 row_mask:0xf bank_mask:0xf bound_ctrl:1
	ds_read_b128 v[104:107], v34 offset:9984
	s_nop 0
	v_add_f32_dpp v30, v15, v15 row_ror:1 row_mask:0xf bank_mask:0xf bound_ctrl:1
	s_waitcnt lgkmcnt(9)
	v_pk_fma_f32 v[10:11], v[128:129], v[30:31], v[16:17] op_sel_hi:[1,0,1] neg_lo:[0,1,0] neg_hi:[0,1,0]
	v_pk_fma_f32 v[8:9], v[130:131], v[30:31], v[18:19] op_sel_hi:[1,0,1] neg_lo:[0,1,0] neg_hi:[0,1,0]
	v_pk_mul_f32 v[26:27], v[10:11], v[132:133] op_sel:[0,0] op_sel_hi:[0,1]
	v_pk_fma_f32 v[26:27], v[10:11], v[134:135], v[26:27] op_sel:[1,0,0] op_sel_hi:[1,1,1]
	v_pk_fma_f32 v[26:27], v[8:9], v[136:137], v[26:27] op_sel:[0,0,0] op_sel_hi:[0,1,1]
	v_pk_fma_f32 v[26:27], v[8:9], v[138:139], v[26:27] op_sel:[1,0,0] op_sel_hi:[1,1,1]
	v_pk_fma_f32 v[16:17], v[76:77], v[156:157], v[10:11] op_sel_hi:[1,0,1]
	v_pk_fma_f32 v[18:19], v[78:79], v[156:157], v[8:9] op_sel_hi:[1,0,1]
	v_add_f32_dpp v15, v26, v26 row_ror:8 row_mask:0xf bank_mask:0xf bound_ctrl:1
	ds_read_b128 v[124:127], v34 offset:11264
	s_nop 0
	v_add_f32_dpp v15, v15, v15 row_ror:4 row_mask:0xf bank_mask:0xf bound_ctrl:1
	ds_read_b128 v[112:115], v34 offset:10496
	ds_read_b128 v[116:119], v34 offset:10752
	v_add_f32_dpp v15, v15, v15 row_ror:2 row_mask:0xf bank_mask:0xf bound_ctrl:1
	ds_read_b128 v[120:123], v34 offset:11008
	ds_write2st64_b32 v37, v25, v27 offset0:24 offset1:28
	v_add_f32_dpp v30, v15, v15 row_ror:1 row_mask:0xf bank_mask:0xf bound_ctrl:1
	s_waitcnt lgkmcnt(9)
	v_pk_fma_f32 v[10:11], v[80:81], v[30:31], v[16:17] op_sel_hi:[1,0,1] neg_lo:[0,1,0] neg_hi:[0,1,0]
	v_pk_fma_f32 v[8:9], v[82:83], v[30:31], v[18:19] op_sel_hi:[1,0,1] neg_lo:[0,1,0] neg_hi:[0,1,0]
	v_pk_mul_f32 v[24:25], v[10:11], v[84:85] op_sel:[0,0] op_sel_hi:[0,1]
	v_pk_fma_f32 v[24:25], v[10:11], v[86:87], v[24:25] op_sel:[1,0,0] op_sel_hi:[1,1,1]
	v_pk_fma_f32 v[24:25], v[8:9], v[88:89], v[24:25] op_sel:[0,0,0] op_sel_hi:[0,1,1]
	v_pk_fma_f32 v[24:25], v[8:9], v[90:91], v[24:25] op_sel:[1,0,0] op_sel_hi:[1,1,1]
	v_pk_fma_f32 v[16:17], v[92:93], v[156:157], v[10:11] op_sel:[0,1,0] op_sel_hi:[1,1,1]
	v_pk_fma_f32 v[18:19], v[94:95], v[156:157], v[8:9] op_sel:[0,1,0] op_sel_hi:[1,1,1]
	v_add_f32_dpp v15, v24, v24 row_ror:8 row_mask:0xf bank_mask:0xf bound_ctrl:1
	ds_read_b128 v[76:79], v34 offset:12288
	s_nop 0
	v_add_f32_dpp v15, v15, v15 row_ror:4 row_mask:0xf bank_mask:0xf bound_ctrl:1
	ds_read_b128 v[128:131], v34 offset:11520
	ds_read_b128 v[132:135], v34 offset:11776
	v_add_f32_dpp v15, v15, v15 row_ror:2 row_mask:0xf bank_mask:0xf bound_ctrl:1
	ds_read_b128 v[136:139], v34 offset:12032
	ds_read_b128 v[160:163], v35 offset:48
	v_add_f32_dpp v30, v15, v15 row_ror:1 row_mask:0xf bank_mask:0xf bound_ctrl:1
	s_waitcnt lgkmcnt(10)
	v_pk_fma_f32 v[10:11], v[96:97], v[30:31], v[16:17] op_sel_hi:[1,0,1] neg_lo:[0,1,0] neg_hi:[0,1,0]
	v_pk_fma_f32 v[8:9], v[98:99], v[30:31], v[18:19] op_sel_hi:[1,0,1] neg_lo:[0,1,0] neg_hi:[0,1,0]
	v_pk_mul_f32 v[26:27], v[10:11], v[100:101] op_sel:[0,0] op_sel_hi:[0,1]
	v_pk_fma_f32 v[26:27], v[10:11], v[102:103], v[26:27] op_sel:[1,0,0] op_sel_hi:[1,1,1]
	v_pk_fma_f32 v[26:27], v[8:9], v[104:105], v[26:27] op_sel:[0,0,0] op_sel_hi:[0,1,1]
	v_pk_fma_f32 v[26:27], v[8:9], v[106:107], v[26:27] op_sel:[1,0,0] op_sel_hi:[1,1,1]
	v_pk_fma_f32 v[16:17], v[108:109], v[158:159], v[10:11] op_sel_hi:[1,0,1]
	v_pk_fma_f32 v[18:19], v[110:111], v[158:159], v[8:9] op_sel_hi:[1,0,1]
	v_add_f32_dpp v15, v26, v26 row_ror:8 row_mask:0xf bank_mask:0xf bound_ctrl:1
	ds_read_b128 v[92:95], v34 offset:13312
	s_nop 0
	v_add_f32_dpp v15, v15, v15 row_ror:4 row_mask:0xf bank_mask:0xf bound_ctrl:1
	ds_read_b128 v[80:83], v34 offset:12544
	ds_read_b128 v[84:87], v34 offset:12800
	v_add_f32_dpp v15, v15, v15 row_ror:2 row_mask:0xf bank_mask:0xf bound_ctrl:1
	ds_read_b128 v[88:91], v34 offset:13056
	ds_write2st64_b32 v37, v25, v27 offset0:32 offset1:36
	v_add_f32_dpp v30, v15, v15 row_ror:1 row_mask:0xf bank_mask:0xf bound_ctrl:1
	s_waitcnt lgkmcnt(10)
	v_pk_fma_f32 v[10:11], v[112:113], v[30:31], v[16:17] op_sel_hi:[1,0,1] neg_lo:[0,1,0] neg_hi:[0,1,0]
	v_pk_fma_f32 v[8:9], v[114:115], v[30:31], v[18:19] op_sel_hi:[1,0,1] neg_lo:[0,1,0] neg_hi:[0,1,0]
	v_pk_mul_f32 v[24:25], v[10:11], v[116:117] op_sel:[0,0] op_sel_hi:[0,1]
	v_pk_fma_f32 v[24:25], v[10:11], v[118:119], v[24:25] op_sel:[1,0,0] op_sel_hi:[1,1,1]
	v_pk_fma_f32 v[24:25], v[8:9], v[120:121], v[24:25] op_sel:[0,0,0] op_sel_hi:[0,1,1]
	v_pk_fma_f32 v[24:25], v[8:9], v[122:123], v[24:25] op_sel:[1,0,0] op_sel_hi:[1,1,1]
	v_pk_fma_f32 v[16:17], v[124:125], v[158:159], v[10:11] op_sel:[0,1,0] op_sel_hi:[1,1,1]
	v_pk_fma_f32 v[18:19], v[126:127], v[158:159], v[8:9] op_sel:[0,1,0] op_sel_hi:[1,1,1]
	v_add_f32_dpp v15, v24, v24 row_ror:8 row_mask:0xf bank_mask:0xf bound_ctrl:1
	ds_read_b128 v[108:111], v34 offset:14336
	s_nop 0
	v_add_f32_dpp v15, v15, v15 row_ror:4 row_mask:0xf bank_mask:0xf bound_ctrl:1
	ds_read_b128 v[96:99], v34 offset:13568
	ds_read_b128 v[100:103], v34 offset:13824
	v_add_f32_dpp v15, v15, v15 row_ror:2 row_mask:0xf bank_mask:0xf bound_ctrl:1
	ds_read_b128 v[104:107], v34 offset:14080
	s_nop 0
	v_add_f32_dpp v30, v15, v15 row_ror:1 row_mask:0xf bank_mask:0xf bound_ctrl:1
	s_waitcnt lgkmcnt(9)
	v_pk_fma_f32 v[10:11], v[128:129], v[30:31], v[16:17] op_sel_hi:[1,0,1] neg_lo:[0,1,0] neg_hi:[0,1,0]
	v_pk_fma_f32 v[8:9], v[130:131], v[30:31], v[18:19] op_sel_hi:[1,0,1] neg_lo:[0,1,0] neg_hi:[0,1,0]
	v_pk_mul_f32 v[26:27], v[10:11], v[132:133] op_sel:[0,0] op_sel_hi:[0,1]
	v_pk_fma_f32 v[26:27], v[10:11], v[134:135], v[26:27] op_sel:[1,0,0] op_sel_hi:[1,1,1]
	v_pk_fma_f32 v[26:27], v[8:9], v[136:137], v[26:27] op_sel:[0,0,0] op_sel_hi:[0,1,1]
	v_pk_fma_f32 v[26:27], v[8:9], v[138:139], v[26:27] op_sel:[1,0,0] op_sel_hi:[1,1,1]
	v_pk_fma_f32 v[16:17], v[76:77], v[160:161], v[10:11] op_sel_hi:[1,0,1]
	v_pk_fma_f32 v[18:19], v[78:79], v[160:161], v[8:9] op_sel_hi:[1,0,1]
	v_add_f32_dpp v15, v26, v26 row_ror:8 row_mask:0xf bank_mask:0xf bound_ctrl:1
	ds_read_b128 v[124:127], v34 offset:15360
	s_nop 0
	v_add_f32_dpp v15, v15, v15 row_ror:4 row_mask:0xf bank_mask:0xf bound_ctrl:1
	ds_read_b128 v[112:115], v34 offset:14592
	ds_read_b128 v[116:119], v34 offset:14848
	v_add_f32_dpp v15, v15, v15 row_ror:2 row_mask:0xf bank_mask:0xf bound_ctrl:1
	ds_read_b128 v[120:123], v34 offset:15104
	ds_write2st64_b32 v37, v25, v27 offset0:40 offset1:44
	v_add_f32_dpp v30, v15, v15 row_ror:1 row_mask:0xf bank_mask:0xf bound_ctrl:1
	s_waitcnt lgkmcnt(9)
	v_pk_fma_f32 v[10:11], v[80:81], v[30:31], v[16:17] op_sel_hi:[1,0,1] neg_lo:[0,1,0] neg_hi:[0,1,0]
	v_pk_fma_f32 v[8:9], v[82:83], v[30:31], v[18:19] op_sel_hi:[1,0,1] neg_lo:[0,1,0] neg_hi:[0,1,0]
	v_pk_mul_f32 v[24:25], v[10:11], v[84:85] op_sel:[0,0] op_sel_hi:[0,1]
	v_pk_fma_f32 v[24:25], v[10:11], v[86:87], v[24:25] op_sel:[1,0,0] op_sel_hi:[1,1,1]
	v_pk_fma_f32 v[24:25], v[8:9], v[88:89], v[24:25] op_sel:[0,0,0] op_sel_hi:[0,1,1]
	v_pk_fma_f32 v[24:25], v[8:9], v[90:91], v[24:25] op_sel:[1,0,0] op_sel_hi:[1,1,1]
	v_pk_fma_f32 v[16:17], v[92:93], v[160:161], v[10:11] op_sel:[0,1,0] op_sel_hi:[1,1,1]
	v_pk_fma_f32 v[18:19], v[94:95], v[160:161], v[8:9] op_sel:[0,1,0] op_sel_hi:[1,1,1]
	v_add_f32_dpp v15, v24, v24 row_ror:8 row_mask:0xf bank_mask:0xf bound_ctrl:1
	ds_read_b128 v[76:79], v34 offset:16384
	s_nop 0
	v_add_f32_dpp v15, v15, v15 row_ror:4 row_mask:0xf bank_mask:0xf bound_ctrl:1
	ds_read_b128 v[128:131], v34 offset:15616
	ds_read_b128 v[132:135], v34 offset:15872
	v_add_f32_dpp v15, v15, v15 row_ror:2 row_mask:0xf bank_mask:0xf bound_ctrl:1
	ds_read_b128 v[136:139], v34 offset:16128
	ds_read_b128 v[156:159], v35 offset:64
	v_add_f32_dpp v30, v15, v15 row_ror:1 row_mask:0xf bank_mask:0xf bound_ctrl:1
	s_waitcnt lgkmcnt(10)
	v_pk_fma_f32 v[10:11], v[96:97], v[30:31], v[16:17] op_sel_hi:[1,0,1] neg_lo:[0,1,0] neg_hi:[0,1,0]
	v_pk_fma_f32 v[8:9], v[98:99], v[30:31], v[18:19] op_sel_hi:[1,0,1] neg_lo:[0,1,0] neg_hi:[0,1,0]
	v_pk_mul_f32 v[26:27], v[10:11], v[100:101] op_sel:[0,0] op_sel_hi:[0,1]
	v_pk_fma_f32 v[26:27], v[10:11], v[102:103], v[26:27] op_sel:[1,0,0] op_sel_hi:[1,1,1]
	v_pk_fma_f32 v[26:27], v[8:9], v[104:105], v[26:27] op_sel:[0,0,0] op_sel_hi:[0,1,1]
	v_pk_fma_f32 v[26:27], v[8:9], v[106:107], v[26:27] op_sel:[1,0,0] op_sel_hi:[1,1,1]
	v_pk_fma_f32 v[16:17], v[108:109], v[162:163], v[10:11] op_sel_hi:[1,0,1]
	v_pk_fma_f32 v[18:19], v[110:111], v[162:163], v[8:9] op_sel_hi:[1,0,1]
	v_add_f32_dpp v15, v26, v26 row_ror:8 row_mask:0xf bank_mask:0xf bound_ctrl:1
	ds_read_b128 v[92:95], v34 offset:17408
	s_nop 0
	v_add_f32_dpp v15, v15, v15 row_ror:4 row_mask:0xf bank_mask:0xf bound_ctrl:1
	ds_read_b128 v[80:83], v34 offset:16640
	ds_read_b128 v[84:87], v34 offset:16896
	v_add_f32_dpp v15, v15, v15 row_ror:2 row_mask:0xf bank_mask:0xf bound_ctrl:1
	ds_read_b128 v[88:91], v34 offset:17152
	ds_write2st64_b32 v37, v25, v27 offset0:48 offset1:52
	v_add_f32_dpp v30, v15, v15 row_ror:1 row_mask:0xf bank_mask:0xf bound_ctrl:1
	s_waitcnt lgkmcnt(10)
	v_pk_fma_f32 v[10:11], v[112:113], v[30:31], v[16:17] op_sel_hi:[1,0,1] neg_lo:[0,1,0] neg_hi:[0,1,0]
	v_pk_fma_f32 v[8:9], v[114:115], v[30:31], v[18:19] op_sel_hi:[1,0,1] neg_lo:[0,1,0] neg_hi:[0,1,0]
	v_pk_mul_f32 v[24:25], v[10:11], v[116:117] op_sel:[0,0] op_sel_hi:[0,1]
	v_pk_fma_f32 v[24:25], v[10:11], v[118:119], v[24:25] op_sel:[1,0,0] op_sel_hi:[1,1,1]
	v_pk_fma_f32 v[24:25], v[8:9], v[120:121], v[24:25] op_sel:[0,0,0] op_sel_hi:[0,1,1]
	v_pk_fma_f32 v[24:25], v[8:9], v[122:123], v[24:25] op_sel:[1,0,0] op_sel_hi:[1,1,1]
	v_pk_fma_f32 v[16:17], v[124:125], v[162:163], v[10:11] op_sel:[0,1,0] op_sel_hi:[1,1,1]
	v_pk_fma_f32 v[18:19], v[126:127], v[162:163], v[8:9] op_sel:[0,1,0] op_sel_hi:[1,1,1]
	v_add_f32_dpp v15, v24, v24 row_ror:8 row_mask:0xf bank_mask:0xf bound_ctrl:1
	ds_read_b128 v[108:111], v34 offset:18432
	s_nop 0
	v_add_f32_dpp v15, v15, v15 row_ror:4 row_mask:0xf bank_mask:0xf bound_ctrl:1
	ds_read_b128 v[96:99], v34 offset:17664
	ds_read_b128 v[100:103], v34 offset:17920
	v_add_f32_dpp v15, v15, v15 row_ror:2 row_mask:0xf bank_mask:0xf bound_ctrl:1
	ds_read_b128 v[104:107], v34 offset:18176
	s_nop 0
	v_add_f32_dpp v30, v15, v15 row_ror:1 row_mask:0xf bank_mask:0xf bound_ctrl:1
	s_waitcnt lgkmcnt(9)
	v_pk_fma_f32 v[10:11], v[128:129], v[30:31], v[16:17] op_sel_hi:[1,0,1] neg_lo:[0,1,0] neg_hi:[0,1,0]
	v_pk_fma_f32 v[8:9], v[130:131], v[30:31], v[18:19] op_sel_hi:[1,0,1] neg_lo:[0,1,0] neg_hi:[0,1,0]
	v_pk_mul_f32 v[26:27], v[10:11], v[132:133] op_sel:[0,0] op_sel_hi:[0,1]
	v_pk_fma_f32 v[26:27], v[10:11], v[134:135], v[26:27] op_sel:[1,0,0] op_sel_hi:[1,1,1]
	v_pk_fma_f32 v[26:27], v[8:9], v[136:137], v[26:27] op_sel:[0,0,0] op_sel_hi:[0,1,1]
	v_pk_fma_f32 v[26:27], v[8:9], v[138:139], v[26:27] op_sel:[1,0,0] op_sel_hi:[1,1,1]
	v_pk_fma_f32 v[16:17], v[76:77], v[156:157], v[10:11] op_sel_hi:[1,0,1]
	v_pk_fma_f32 v[18:19], v[78:79], v[156:157], v[8:9] op_sel_hi:[1,0,1]
	v_add_f32_dpp v15, v26, v26 row_ror:8 row_mask:0xf bank_mask:0xf bound_ctrl:1
	ds_read_b128 v[124:127], v34 offset:19456
	s_nop 0
	v_add_f32_dpp v15, v15, v15 row_ror:4 row_mask:0xf bank_mask:0xf bound_ctrl:1
	ds_read_b128 v[112:115], v34 offset:18688
	ds_read_b128 v[116:119], v34 offset:18944
	v_add_f32_dpp v15, v15, v15 row_ror:2 row_mask:0xf bank_mask:0xf bound_ctrl:1
	ds_read_b128 v[120:123], v34 offset:19200
	ds_write2st64_b32 v37, v25, v27 offset0:56 offset1:60
	v_add_f32_dpp v30, v15, v15 row_ror:1 row_mask:0xf bank_mask:0xf bound_ctrl:1
	s_waitcnt lgkmcnt(9)
	v_pk_fma_f32 v[10:11], v[80:81], v[30:31], v[16:17] op_sel_hi:[1,0,1] neg_lo:[0,1,0] neg_hi:[0,1,0]
	v_pk_fma_f32 v[8:9], v[82:83], v[30:31], v[18:19] op_sel_hi:[1,0,1] neg_lo:[0,1,0] neg_hi:[0,1,0]
	v_pk_mul_f32 v[24:25], v[10:11], v[84:85] op_sel:[0,0] op_sel_hi:[0,1]
	v_pk_fma_f32 v[24:25], v[10:11], v[86:87], v[24:25] op_sel:[1,0,0] op_sel_hi:[1,1,1]
	v_pk_fma_f32 v[24:25], v[8:9], v[88:89], v[24:25] op_sel:[0,0,0] op_sel_hi:[0,1,1]
	v_pk_fma_f32 v[24:25], v[8:9], v[90:91], v[24:25] op_sel:[1,0,0] op_sel_hi:[1,1,1]
	v_pk_fma_f32 v[16:17], v[92:93], v[156:157], v[10:11] op_sel:[0,1,0] op_sel_hi:[1,1,1]
	v_pk_fma_f32 v[18:19], v[94:95], v[156:157], v[8:9] op_sel:[0,1,0] op_sel_hi:[1,1,1]
	v_add_f32_dpp v15, v24, v24 row_ror:8 row_mask:0xf bank_mask:0xf bound_ctrl:1
	ds_read_b128 v[76:79], v34 offset:20480
	s_nop 0
	v_add_f32_dpp v15, v15, v15 row_ror:4 row_mask:0xf bank_mask:0xf bound_ctrl:1
	ds_read_b128 v[128:131], v34 offset:19712
	ds_read_b128 v[132:135], v34 offset:19968
	v_add_f32_dpp v15, v15, v15 row_ror:2 row_mask:0xf bank_mask:0xf bound_ctrl:1
	ds_read_b128 v[136:139], v34 offset:20224
	ds_read_b128 v[160:163], v35 offset:80
	v_add_f32_dpp v30, v15, v15 row_ror:1 row_mask:0xf bank_mask:0xf bound_ctrl:1
	s_waitcnt lgkmcnt(10)
	v_pk_fma_f32 v[10:11], v[96:97], v[30:31], v[16:17] op_sel_hi:[1,0,1] neg_lo:[0,1,0] neg_hi:[0,1,0]
	v_pk_fma_f32 v[8:9], v[98:99], v[30:31], v[18:19] op_sel_hi:[1,0,1] neg_lo:[0,1,0] neg_hi:[0,1,0]
	v_pk_mul_f32 v[26:27], v[10:11], v[100:101] op_sel:[0,0] op_sel_hi:[0,1]
	v_pk_fma_f32 v[26:27], v[10:11], v[102:103], v[26:27] op_sel:[1,0,0] op_sel_hi:[1,1,1]
	v_pk_fma_f32 v[26:27], v[8:9], v[104:105], v[26:27] op_sel:[0,0,0] op_sel_hi:[0,1,1]
	v_pk_fma_f32 v[26:27], v[8:9], v[106:107], v[26:27] op_sel:[1,0,0] op_sel_hi:[1,1,1]
	v_pk_fma_f32 v[16:17], v[108:109], v[158:159], v[10:11] op_sel_hi:[1,0,1]
	v_pk_fma_f32 v[18:19], v[110:111], v[158:159], v[8:9] op_sel_hi:[1,0,1]
	v_add_f32_dpp v15, v26, v26 row_ror:8 row_mask:0xf bank_mask:0xf bound_ctrl:1
	ds_read_b128 v[92:95], v34 offset:21504
	s_nop 0
	v_add_f32_dpp v15, v15, v15 row_ror:4 row_mask:0xf bank_mask:0xf bound_ctrl:1
	ds_read_b128 v[80:83], v34 offset:20736
	ds_read_b128 v[84:87], v34 offset:20992
	v_add_f32_dpp v15, v15, v15 row_ror:2 row_mask:0xf bank_mask:0xf bound_ctrl:1
	ds_read_b128 v[88:91], v34 offset:21248
	ds_write2st64_b32 v37, v25, v27 offset0:64 offset1:68
	v_add_f32_dpp v30, v15, v15 row_ror:1 row_mask:0xf bank_mask:0xf bound_ctrl:1
	s_waitcnt lgkmcnt(10)
	v_pk_fma_f32 v[10:11], v[112:113], v[30:31], v[16:17] op_sel_hi:[1,0,1] neg_lo:[0,1,0] neg_hi:[0,1,0]
	v_pk_fma_f32 v[8:9], v[114:115], v[30:31], v[18:19] op_sel_hi:[1,0,1] neg_lo:[0,1,0] neg_hi:[0,1,0]
	v_pk_mul_f32 v[24:25], v[10:11], v[116:117] op_sel:[0,0] op_sel_hi:[0,1]
	v_pk_fma_f32 v[24:25], v[10:11], v[118:119], v[24:25] op_sel:[1,0,0] op_sel_hi:[1,1,1]
	v_pk_fma_f32 v[24:25], v[8:9], v[120:121], v[24:25] op_sel:[0,0,0] op_sel_hi:[0,1,1]
	v_pk_fma_f32 v[24:25], v[8:9], v[122:123], v[24:25] op_sel:[1,0,0] op_sel_hi:[1,1,1]
	v_pk_fma_f32 v[16:17], v[124:125], v[158:159], v[10:11] op_sel:[0,1,0] op_sel_hi:[1,1,1]
	v_pk_fma_f32 v[18:19], v[126:127], v[158:159], v[8:9] op_sel:[0,1,0] op_sel_hi:[1,1,1]
	v_add_f32_dpp v15, v24, v24 row_ror:8 row_mask:0xf bank_mask:0xf bound_ctrl:1
	ds_read_b128 v[108:111], v34 offset:22528
	s_nop 0
	v_add_f32_dpp v15, v15, v15 row_ror:4 row_mask:0xf bank_mask:0xf bound_ctrl:1
	ds_read_b128 v[96:99], v34 offset:21760
	ds_read_b128 v[100:103], v34 offset:22016
	v_add_f32_dpp v15, v15, v15 row_ror:2 row_mask:0xf bank_mask:0xf bound_ctrl:1
	ds_read_b128 v[104:107], v34 offset:22272
	s_nop 0
	v_add_f32_dpp v30, v15, v15 row_ror:1 row_mask:0xf bank_mask:0xf bound_ctrl:1
	s_waitcnt lgkmcnt(9)
	v_pk_fma_f32 v[10:11], v[128:129], v[30:31], v[16:17] op_sel_hi:[1,0,1] neg_lo:[0,1,0] neg_hi:[0,1,0]
	v_pk_fma_f32 v[8:9], v[130:131], v[30:31], v[18:19] op_sel_hi:[1,0,1] neg_lo:[0,1,0] neg_hi:[0,1,0]
	v_pk_mul_f32 v[26:27], v[10:11], v[132:133] op_sel:[0,0] op_sel_hi:[0,1]
	v_pk_fma_f32 v[26:27], v[10:11], v[134:135], v[26:27] op_sel:[1,0,0] op_sel_hi:[1,1,1]
	v_pk_fma_f32 v[26:27], v[8:9], v[136:137], v[26:27] op_sel:[0,0,0] op_sel_hi:[0,1,1]
	v_pk_fma_f32 v[26:27], v[8:9], v[138:139], v[26:27] op_sel:[1,0,0] op_sel_hi:[1,1,1]
	v_pk_fma_f32 v[16:17], v[76:77], v[160:161], v[10:11] op_sel_hi:[1,0,1]
	v_pk_fma_f32 v[18:19], v[78:79], v[160:161], v[8:9] op_sel_hi:[1,0,1]
	v_add_f32_dpp v15, v26, v26 row_ror:8 row_mask:0xf bank_mask:0xf bound_ctrl:1
	ds_read_b128 v[124:127], v34 offset:23552
	s_nop 0
	v_add_f32_dpp v15, v15, v15 row_ror:4 row_mask:0xf bank_mask:0xf bound_ctrl:1
	ds_read_b128 v[112:115], v34 offset:22784
	ds_read_b128 v[116:119], v34 offset:23040
	v_add_f32_dpp v15, v15, v15 row_ror:2 row_mask:0xf bank_mask:0xf bound_ctrl:1
	ds_read_b128 v[120:123], v34 offset:23296
	ds_write2st64_b32 v37, v25, v27 offset0:72 offset1:76
	v_add_f32_dpp v30, v15, v15 row_ror:1 row_mask:0xf bank_mask:0xf bound_ctrl:1
	s_waitcnt lgkmcnt(9)
	v_pk_fma_f32 v[10:11], v[80:81], v[30:31], v[16:17] op_sel_hi:[1,0,1] neg_lo:[0,1,0] neg_hi:[0,1,0]
	v_pk_fma_f32 v[8:9], v[82:83], v[30:31], v[18:19] op_sel_hi:[1,0,1] neg_lo:[0,1,0] neg_hi:[0,1,0]
	v_pk_mul_f32 v[24:25], v[10:11], v[84:85] op_sel:[0,0] op_sel_hi:[0,1]
	v_pk_fma_f32 v[24:25], v[10:11], v[86:87], v[24:25] op_sel:[1,0,0] op_sel_hi:[1,1,1]
	v_pk_fma_f32 v[24:25], v[8:9], v[88:89], v[24:25] op_sel:[0,0,0] op_sel_hi:[0,1,1]
	v_pk_fma_f32 v[24:25], v[8:9], v[90:91], v[24:25] op_sel:[1,0,0] op_sel_hi:[1,1,1]
	v_pk_fma_f32 v[16:17], v[92:93], v[160:161], v[10:11] op_sel:[0,1,0] op_sel_hi:[1,1,1]
	v_pk_fma_f32 v[18:19], v[94:95], v[160:161], v[8:9] op_sel:[0,1,0] op_sel_hi:[1,1,1]
	v_add_f32_dpp v15, v24, v24 row_ror:8 row_mask:0xf bank_mask:0xf bound_ctrl:1
	ds_read_b128 v[76:79], v34 offset:24576
	s_nop 0
	v_add_f32_dpp v15, v15, v15 row_ror:4 row_mask:0xf bank_mask:0xf bound_ctrl:1
	ds_read_b128 v[128:131], v34 offset:23808
	ds_read_b128 v[132:135], v34 offset:24064
	v_add_f32_dpp v15, v15, v15 row_ror:2 row_mask:0xf bank_mask:0xf bound_ctrl:1
	ds_read_b128 v[136:139], v34 offset:24320
	ds_read_b128 v[156:159], v35 offset:96
	v_add_f32_dpp v30, v15, v15 row_ror:1 row_mask:0xf bank_mask:0xf bound_ctrl:1
	s_waitcnt lgkmcnt(10)
	v_pk_fma_f32 v[10:11], v[96:97], v[30:31], v[16:17] op_sel_hi:[1,0,1] neg_lo:[0,1,0] neg_hi:[0,1,0]
	v_pk_fma_f32 v[8:9], v[98:99], v[30:31], v[18:19] op_sel_hi:[1,0,1] neg_lo:[0,1,0] neg_hi:[0,1,0]
	v_pk_mul_f32 v[26:27], v[10:11], v[100:101] op_sel:[0,0] op_sel_hi:[0,1]
	v_pk_fma_f32 v[26:27], v[10:11], v[102:103], v[26:27] op_sel:[1,0,0] op_sel_hi:[1,1,1]
	v_pk_fma_f32 v[26:27], v[8:9], v[104:105], v[26:27] op_sel:[0,0,0] op_sel_hi:[0,1,1]
	v_pk_fma_f32 v[26:27], v[8:9], v[106:107], v[26:27] op_sel:[1,0,0] op_sel_hi:[1,1,1]
	v_pk_fma_f32 v[16:17], v[108:109], v[162:163], v[10:11] op_sel_hi:[1,0,1]
	v_pk_fma_f32 v[18:19], v[110:111], v[162:163], v[8:9] op_sel_hi:[1,0,1]
	v_add_f32_dpp v15, v26, v26 row_ror:8 row_mask:0xf bank_mask:0xf bound_ctrl:1
	ds_read_b128 v[92:95], v34 offset:25600
	s_nop 0
	v_add_f32_dpp v15, v15, v15 row_ror:4 row_mask:0xf bank_mask:0xf bound_ctrl:1
	ds_read_b128 v[80:83], v34 offset:24832
	ds_read_b128 v[84:87], v34 offset:25088
	v_add_f32_dpp v15, v15, v15 row_ror:2 row_mask:0xf bank_mask:0xf bound_ctrl:1
	ds_read_b128 v[88:91], v34 offset:25344
	ds_write2st64_b32 v37, v25, v27 offset0:80 offset1:84
	v_add_f32_dpp v30, v15, v15 row_ror:1 row_mask:0xf bank_mask:0xf bound_ctrl:1
	s_waitcnt lgkmcnt(10)
	v_pk_fma_f32 v[10:11], v[112:113], v[30:31], v[16:17] op_sel_hi:[1,0,1] neg_lo:[0,1,0] neg_hi:[0,1,0]
	v_pk_fma_f32 v[8:9], v[114:115], v[30:31], v[18:19] op_sel_hi:[1,0,1] neg_lo:[0,1,0] neg_hi:[0,1,0]
	v_pk_mul_f32 v[24:25], v[10:11], v[116:117] op_sel:[0,0] op_sel_hi:[0,1]
	v_pk_fma_f32 v[24:25], v[10:11], v[118:119], v[24:25] op_sel:[1,0,0] op_sel_hi:[1,1,1]
	v_pk_fma_f32 v[24:25], v[8:9], v[120:121], v[24:25] op_sel:[0,0,0] op_sel_hi:[0,1,1]
	v_pk_fma_f32 v[24:25], v[8:9], v[122:123], v[24:25] op_sel:[1,0,0] op_sel_hi:[1,1,1]
	v_pk_fma_f32 v[16:17], v[124:125], v[162:163], v[10:11] op_sel:[0,1,0] op_sel_hi:[1,1,1]
	v_pk_fma_f32 v[18:19], v[126:127], v[162:163], v[8:9] op_sel:[0,1,0] op_sel_hi:[1,1,1]
	v_add_f32_dpp v15, v24, v24 row_ror:8 row_mask:0xf bank_mask:0xf bound_ctrl:1
	ds_read_b128 v[108:111], v34 offset:26624
	s_nop 0
	v_add_f32_dpp v15, v15, v15 row_ror:4 row_mask:0xf bank_mask:0xf bound_ctrl:1
	ds_read_b128 v[96:99], v34 offset:25856
	ds_read_b128 v[100:103], v34 offset:26112
	v_add_f32_dpp v15, v15, v15 row_ror:2 row_mask:0xf bank_mask:0xf bound_ctrl:1
	ds_read_b128 v[104:107], v34 offset:26368
	s_nop 0
	v_add_f32_dpp v30, v15, v15 row_ror:1 row_mask:0xf bank_mask:0xf bound_ctrl:1
	s_waitcnt lgkmcnt(9)
	v_pk_fma_f32 v[10:11], v[128:129], v[30:31], v[16:17] op_sel_hi:[1,0,1] neg_lo:[0,1,0] neg_hi:[0,1,0]
	v_pk_fma_f32 v[8:9], v[130:131], v[30:31], v[18:19] op_sel_hi:[1,0,1] neg_lo:[0,1,0] neg_hi:[0,1,0]
	v_pk_mul_f32 v[26:27], v[10:11], v[132:133] op_sel:[0,0] op_sel_hi:[0,1]
	v_pk_fma_f32 v[26:27], v[10:11], v[134:135], v[26:27] op_sel:[1,0,0] op_sel_hi:[1,1,1]
	v_pk_fma_f32 v[26:27], v[8:9], v[136:137], v[26:27] op_sel:[0,0,0] op_sel_hi:[0,1,1]
	v_pk_fma_f32 v[26:27], v[8:9], v[138:139], v[26:27] op_sel:[1,0,0] op_sel_hi:[1,1,1]
	v_pk_fma_f32 v[16:17], v[76:77], v[156:157], v[10:11] op_sel_hi:[1,0,1]
	v_pk_fma_f32 v[18:19], v[78:79], v[156:157], v[8:9] op_sel_hi:[1,0,1]
	v_add_f32_dpp v15, v26, v26 row_ror:8 row_mask:0xf bank_mask:0xf bound_ctrl:1
	ds_read_b128 v[124:127], v34 offset:27648
	s_nop 0
	v_add_f32_dpp v15, v15, v15 row_ror:4 row_mask:0xf bank_mask:0xf bound_ctrl:1
	ds_read_b128 v[112:115], v34 offset:26880
	ds_read_b128 v[116:119], v34 offset:27136
	v_add_f32_dpp v15, v15, v15 row_ror:2 row_mask:0xf bank_mask:0xf bound_ctrl:1
	ds_read_b128 v[120:123], v34 offset:27392
	ds_write2st64_b32 v37, v25, v27 offset0:88 offset1:92
	v_add_f32_dpp v30, v15, v15 row_ror:1 row_mask:0xf bank_mask:0xf bound_ctrl:1
	s_waitcnt lgkmcnt(9)
	v_pk_fma_f32 v[10:11], v[80:81], v[30:31], v[16:17] op_sel_hi:[1,0,1] neg_lo:[0,1,0] neg_hi:[0,1,0]
	v_pk_fma_f32 v[8:9], v[82:83], v[30:31], v[18:19] op_sel_hi:[1,0,1] neg_lo:[0,1,0] neg_hi:[0,1,0]
	v_pk_mul_f32 v[24:25], v[10:11], v[84:85] op_sel:[0,0] op_sel_hi:[0,1]
	v_pk_fma_f32 v[24:25], v[10:11], v[86:87], v[24:25] op_sel:[1,0,0] op_sel_hi:[1,1,1]
	v_pk_fma_f32 v[24:25], v[8:9], v[88:89], v[24:25] op_sel:[0,0,0] op_sel_hi:[0,1,1]
	v_pk_fma_f32 v[24:25], v[8:9], v[90:91], v[24:25] op_sel:[1,0,0] op_sel_hi:[1,1,1]
	v_pk_fma_f32 v[16:17], v[92:93], v[156:157], v[10:11] op_sel:[0,1,0] op_sel_hi:[1,1,1]
	v_pk_fma_f32 v[18:19], v[94:95], v[156:157], v[8:9] op_sel:[0,1,0] op_sel_hi:[1,1,1]
	v_add_f32_dpp v15, v24, v24 row_ror:8 row_mask:0xf bank_mask:0xf bound_ctrl:1
	ds_read_b128 v[76:79], v34 offset:28672
	s_nop 0
	v_add_f32_dpp v15, v15, v15 row_ror:4 row_mask:0xf bank_mask:0xf bound_ctrl:1
	ds_read_b128 v[128:131], v34 offset:27904
	ds_read_b128 v[132:135], v34 offset:28160
	v_add_f32_dpp v15, v15, v15 row_ror:2 row_mask:0xf bank_mask:0xf bound_ctrl:1
	ds_read_b128 v[136:139], v34 offset:28416
	ds_read_b128 v[160:163], v35 offset:112
	v_add_f32_dpp v30, v15, v15 row_ror:1 row_mask:0xf bank_mask:0xf bound_ctrl:1
	ds_read_b128 v[56:59], v52
	s_waitcnt lgkmcnt(10)
	v_pk_fma_f32 v[10:11], v[96:97], v[30:31], v[16:17] op_sel_hi:[1,0,1] neg_lo:[0,1,0] neg_hi:[0,1,0]
	v_pk_fma_f32 v[8:9], v[98:99], v[30:31], v[18:19] op_sel_hi:[1,0,1] neg_lo:[0,1,0] neg_hi:[0,1,0]
	v_pk_mul_f32 v[26:27], v[10:11], v[100:101] op_sel:[0,0] op_sel_hi:[0,1]
	v_pk_fma_f32 v[26:27], v[10:11], v[102:103], v[26:27] op_sel:[1,0,0] op_sel_hi:[1,1,1]
	v_pk_fma_f32 v[26:27], v[8:9], v[104:105], v[26:27] op_sel:[0,0,0] op_sel_hi:[0,1,1]
	v_pk_fma_f32 v[26:27], v[8:9], v[106:107], v[26:27] op_sel:[1,0,0] op_sel_hi:[1,1,1]
	v_pk_fma_f32 v[16:17], v[108:109], v[158:159], v[10:11] op_sel_hi:[1,0,1]
	v_pk_fma_f32 v[18:19], v[110:111], v[158:159], v[8:9] op_sel_hi:[1,0,1]
	v_add_f32_dpp v15, v26, v26 row_ror:8 row_mask:0xf bank_mask:0xf bound_ctrl:1
	ds_read_b128 v[92:95], v34 offset:29696
	s_nop 0
	v_add_f32_dpp v15, v15, v15 row_ror:4 row_mask:0xf bank_mask:0xf bound_ctrl:1
	ds_read_b128 v[80:83], v34 offset:28928
	ds_read_b128 v[84:87], v34 offset:29184
	v_add_f32_dpp v15, v15, v15 row_ror:2 row_mask:0xf bank_mask:0xf bound_ctrl:1
	ds_read_b128 v[88:91], v34 offset:29440
	ds_write2st64_b32 v37, v25, v27 offset0:96 offset1:100
	v_add_f32_dpp v30, v15, v15 row_ror:1 row_mask:0xf bank_mask:0xf bound_ctrl:1
	s_waitcnt lgkmcnt(5)
	v_min_u32_e32 v56, v56, v57
	v_min3_u32 v56, v56, v58, v59
	v_pk_fma_f32 v[10:11], v[112:113], v[30:31], v[16:17] op_sel_hi:[1,0,1] neg_lo:[0,1,0] neg_hi:[0,1,0]
	v_pk_fma_f32 v[8:9], v[114:115], v[30:31], v[18:19] op_sel_hi:[1,0,1] neg_lo:[0,1,0] neg_hi:[0,1,0]
	v_pk_mul_f32 v[24:25], v[10:11], v[116:117] op_sel:[0,0] op_sel_hi:[0,1]
	v_pk_fma_f32 v[24:25], v[10:11], v[118:119], v[24:25] op_sel:[1,0,0] op_sel_hi:[1,1,1]
	v_pk_fma_f32 v[24:25], v[8:9], v[120:121], v[24:25] op_sel:[0,0,0] op_sel_hi:[0,1,1]
	v_pk_fma_f32 v[24:25], v[8:9], v[122:123], v[24:25] op_sel:[1,0,0] op_sel_hi:[1,1,1]
	v_pk_fma_f32 v[16:17], v[124:125], v[158:159], v[10:11] op_sel:[0,1,0] op_sel_hi:[1,1,1]
	v_pk_fma_f32 v[18:19], v[126:127], v[158:159], v[8:9] op_sel:[0,1,0] op_sel_hi:[1,1,1]
	v_add_f32_dpp v15, v24, v24 row_ror:8 row_mask:0xf bank_mask:0xf bound_ctrl:1
	ds_read_b128 v[108:111], v34 offset:30720
	s_nop 0
	v_add_f32_dpp v15, v15, v15 row_ror:4 row_mask:0xf bank_mask:0xf bound_ctrl:1
	ds_read_b128 v[96:99], v34 offset:29952
	ds_read_b128 v[100:103], v34 offset:30208
	v_add_f32_dpp v15, v15, v15 row_ror:2 row_mask:0xf bank_mask:0xf bound_ctrl:1
	ds_read_b128 v[104:107], v34 offset:30464
	s_nop 0
	v_add_f32_dpp v30, v15, v15 row_ror:1 row_mask:0xf bank_mask:0xf bound_ctrl:1
	v_pk_fma_f32 v[10:11], v[128:129], v[30:31], v[16:17] op_sel_hi:[1,0,1] neg_lo:[0,1,0] neg_hi:[0,1,0]
	v_pk_fma_f32 v[8:9], v[130:131], v[30:31], v[18:19] op_sel_hi:[1,0,1] neg_lo:[0,1,0] neg_hi:[0,1,0]
	v_pk_mul_f32 v[26:27], v[10:11], v[132:133] op_sel:[0,0] op_sel_hi:[0,1]
	v_pk_fma_f32 v[26:27], v[10:11], v[134:135], v[26:27] op_sel:[1,0,0] op_sel_hi:[1,1,1]
	v_pk_fma_f32 v[26:27], v[8:9], v[136:137], v[26:27] op_sel:[0,0,0] op_sel_hi:[0,1,1]
	v_pk_fma_f32 v[26:27], v[8:9], v[138:139], v[26:27] op_sel:[1,0,0] op_sel_hi:[1,1,1]
	v_pk_fma_f32 v[16:17], v[76:77], v[160:161], v[10:11] op_sel_hi:[1,0,1]
	v_pk_fma_f32 v[18:19], v[78:79], v[160:161], v[8:9] op_sel_hi:[1,0,1]
	v_add_f32_dpp v15, v26, v26 row_ror:8 row_mask:0xf bank_mask:0xf bound_ctrl:1
	ds_read_b128 v[124:127], v34 offset:31744
	s_nop 0
	v_add_f32_dpp v15, v15, v15 row_ror:4 row_mask:0xf bank_mask:0xf bound_ctrl:1
	ds_read_b128 v[112:115], v34 offset:30976
	ds_read_b128 v[116:119], v34 offset:31232
	v_add_f32_dpp v15, v15, v15 row_ror:2 row_mask:0xf bank_mask:0xf bound_ctrl:1
	ds_read_b128 v[120:123], v34 offset:31488
	ds_read_b128 v[140:143], v34 offset:34560
	ds_write2st64_b32 v37, v25, v27 offset0:104 offset1:108
	v_add_f32_dpp v30, v15, v15 row_ror:1 row_mask:0xf bank_mask:0xf bound_ctrl:1
	v_readfirstlane_b32 s54, v56
	s_add_u32 s64, s6, 2
	s_cmp_lt_u32 s54, s64
	s_cbranch_scc1 .Lss_spin_0
.Lss_ok_0:
	s_waitcnt lgkmcnt(10)
	v_pk_fma_f32 v[10:11], v[80:81], v[30:31], v[16:17] op_sel_hi:[1,0,1] neg_lo:[0,1,0] neg_hi:[0,1,0]
	v_pk_fma_f32 v[8:9], v[82:83], v[30:31], v[18:19] op_sel_hi:[1,0,1] neg_lo:[0,1,0] neg_hi:[0,1,0]
	v_pk_mul_f32 v[24:25], v[10:11], v[84:85] op_sel:[0,0] op_sel_hi:[0,1]
	v_pk_fma_f32 v[24:25], v[10:11], v[86:87], v[24:25] op_sel:[1,0,0] op_sel_hi:[1,1,1]
	v_pk_fma_f32 v[24:25], v[8:9], v[88:89], v[24:25] op_sel:[0,0,0] op_sel_hi:[0,1,1]
	v_pk_fma_f32 v[24:25], v[8:9], v[90:91], v[24:25] op_sel:[1,0,0] op_sel_hi:[1,1,1]
	v_pk_fma_f32 v[16:17], v[92:93], v[160:161], v[10:11] op_sel:[0,1,0] op_sel_hi:[1,1,1]
	v_pk_fma_f32 v[18:19], v[94:95], v[160:161], v[8:9] op_sel:[0,1,0] op_sel_hi:[1,1,1]
	v_add_f32_dpp v15, v24, v24 row_ror:8 row_mask:0xf bank_mask:0xf bound_ctrl:1
	ds_read_b128 v[76:79], v48 offset:0
	s_nop 0
	v_add_f32_dpp v15, v15, v15 row_ror:4 row_mask:0xf bank_mask:0xf bound_ctrl:1
	ds_read_b128 v[128:131], v34 offset:32000
	ds_read_b128 v[132:135], v34 offset:32256
	v_add_f32_dpp v15, v15, v15 row_ror:2 row_mask:0xf bank_mask:0xf bound_ctrl:1
	ds_read_b128 v[136:139], v34 offset:32512
	s_nop 0
	v_add_f32_dpp v30, v15, v15 row_ror:1 row_mask:0xf bank_mask:0xf bound_ctrl:1
	s_waitcnt lgkmcnt(10)
	v_pk_fma_f32 v[10:11], v[96:97], v[30:31], v[16:17] op_sel_hi:[1,0,1] neg_lo:[0,1,0] neg_hi:[0,1,0]
	v_pk_fma_f32 v[8:9], v[98:99], v[30:31], v[18:19] op_sel_hi:[1,0,1] neg_lo:[0,1,0] neg_hi:[0,1,0]
	v_pk_mul_f32 v[26:27], v[10:11], v[100:101] op_sel:[0,0] op_sel_hi:[0,1]
	v_pk_fma_f32 v[26:27], v[10:11], v[102:103], v[26:27] op_sel:[1,0,0] op_sel_hi:[1,1,1]
	v_pk_fma_f32 v[26:27], v[8:9], v[104:105], v[26:27] op_sel:[0,0,0] op_sel_hi:[0,1,1]
	v_pk_fma_f32 v[26:27], v[8:9], v[106:107], v[26:27] op_sel:[1,0,0] op_sel_hi:[1,1,1]
	v_pk_fma_f32 v[16:17], v[108:109], v[162:163], v[10:11] op_sel_hi:[1,0,1]
	v_pk_fma_f32 v[18:19], v[110:111], v[162:163], v[8:9] op_sel_hi:[1,0,1]
	v_add_f32_dpp v15, v26, v26 row_ror:8 row_mask:0xf bank_mask:0xf bound_ctrl:1
	ds_read_b128 v[92:95], v48 offset:1024
	s_nop 0
	v_add_f32_dpp v15, v15, v15 row_ror:4 row_mask:0xf bank_mask:0xf bound_ctrl:1
	ds_read_b128 v[80:83], v48 offset:256
	ds_read_b128 v[84:87], v48 offset:512
	v_add_f32_dpp v15, v15, v15 row_ror:2 row_mask:0xf bank_mask:0xf bound_ctrl:1
	ds_read_b128 v[88:91], v48 offset:768
	ds_read_b128 v[144:147], v48 offset:32768
	ds_write2st64_b32 v37, v25, v27 offset0:112 offset1:116
	v_add_f32_dpp v30, v15, v15 row_ror:1 row_mask:0xf bank_mask:0xf bound_ctrl:1
	ds_read_b128 v[156:159], v49 offset:0
	s_waitcnt lgkmcnt(11)
	v_pk_fma_f32 v[10:11], v[112:113], v[30:31], v[16:17] op_sel_hi:[1,0,1] neg_lo:[0,1,0] neg_hi:[0,1,0]
	v_pk_fma_f32 v[8:9], v[114:115], v[30:31], v[18:19] op_sel_hi:[1,0,1] neg_lo:[0,1,0] neg_hi:[0,1,0]
	v_pk_mul_f32 v[24:25], v[10:11], v[116:117] op_sel:[0,0] op_sel_hi:[0,1]
	v_pk_fma_f32 v[24:25], v[10:11], v[118:119], v[24:25] op_sel:[1,0,0] op_sel_hi:[1,1,1]
	v_pk_fma_f32 v[24:25], v[8:9], v[120:121], v[24:25] op_sel:[0,0,0] op_sel_hi:[0,1,1]
	v_pk_fma_f32 v[24:25], v[8:9], v[122:123], v[24:25] op_sel:[1,0,0] op_sel_hi:[1,1,1]
	v_pk_fma_f32 v[16:17], v[124:125], v[162:163], v[10:11] op_sel:[0,1,0] op_sel_hi:[1,1,1]
	v_pk_fma_f32 v[18:19], v[126:127], v[162:163], v[8:9] op_sel:[0,1,0] op_sel_hi:[1,1,1]
	v_add_f32_dpp v15, v24, v24 row_ror:8 row_mask:0xf bank_mask:0xf bound_ctrl:1
	ds_read_b128 v[108:111], v48 offset:2048
	s_nop 0
	v_add_f32_dpp v15, v15, v15 row_ror:4 row_mask:0xf bank_mask:0xf bound_ctrl:1
	ds_read_b128 v[96:99], v48 offset:1280
	ds_read_b128 v[100:103], v48 offset:1536
	v_add_f32_dpp v15, v15, v15 row_ror:2 row_mask:0xf bank_mask:0xf bound_ctrl:1
	ds_read_b128 v[104:107], v48 offset:1792
	s_nop 0
	v_add_f32_dpp v30, v15, v15 row_ror:1 row_mask:0xf bank_mask:0xf bound_ctrl:1
	s_waitcnt lgkmcnt(11)
	v_pk_fma_f32 v[10:11], v[128:129], v[30:31], v[16:17] op_sel_hi:[1,0,1] neg_lo:[0,1,0] neg_hi:[0,1,0]
	v_pk_fma_f32 v[8:9], v[130:131], v[30:31], v[18:19] op_sel_hi:[1,0,1] neg_lo:[0,1,0] neg_hi:[0,1,0]
	v_pk_mul_f32 v[26:27], v[10:11], v[132:133] op_sel:[0,0] op_sel_hi:[0,1]
	v_pk_fma_f32 v[26:27], v[10:11], v[134:135], v[26:27] op_sel:[1,0,0] op_sel_hi:[1,1,1]
	v_pk_fma_f32 v[26:27], v[8:9], v[136:137], v[26:27] op_sel:[0,0,0] op_sel_hi:[0,1,1]
	v_pk_fma_f32 v[26:27], v[8:9], v[138:139], v[26:27] op_sel:[1,0,0] op_sel_hi:[1,1,1]
	ds_write2st64_b32 v37, v25, v27 offset0:120 offset1:124
	v_pk_mul_f32 v[10:11], v[10:11], v[140:141]
	v_pk_mul_f32 v[8:9], v[8:9], v[142:143]
	s_waitcnt lgkmcnt(7)
	v_pk_mul_f32 v[24:25], v[10:11], v[144:145]
	v_pk_fma_f32 v[24:25], v[8:9], v[146:147], v[24:25]
	v_add_f32_e32 v24, v24, v25
	s_waitcnt lgkmcnt(5)
	v_pk_fma_f32 v[16:17], v[76:77], v[156:157], v[10:11] op_sel_hi:[1,0,1]
	v_pk_fma_f32 v[18:19], v[78:79], v[156:157], v[8:9] op_sel_hi:[1,0,1]
	v_add_f32_dpp v15, v24, v24 row_ror:8 row_mask:0xf bank_mask:0xf bound_ctrl:1
	v_add_u32_e32 v51, 1, v51
	s_add_u32 s6, s6, 1
	v_add_f32_dpp v15, v15, v15 row_ror:4 row_mask:0xf bank_mask:0xf bound_ctrl:1
	ds_write_b32 v53, v51
	ds_read_b128 v[124:127], v48 offset:3072
	v_add_f32_dpp v15, v15, v15 row_ror:2 row_mask:0xf bank_mask:0xf bound_ctrl:1
	ds_read_b128 v[112:115], v48 offset:2304
	ds_read_b128 v[116:119], v48 offset:2560
	v_add_f32_dpp v30, v15, v15 row_ror:1 row_mask:0xf bank_mask:0xf bound_ctrl:1
	ds_read_b128 v[120:123], v48 offset:2816
	v_pk_fma_f32 v[10:11], v[80:81], v[30:31], v[16:17] op_sel_hi:[1,0,1] neg_lo:[0,1,0] neg_hi:[0,1,0]
	v_pk_fma_f32 v[8:9], v[82:83], v[30:31], v[18:19] op_sel_hi:[1,0,1] neg_lo:[0,1,0] neg_hi:[0,1,0]
	v_pk_mul_f32 v[24:25], v[10:11], v[84:85] op_sel:[0,0] op_sel_hi:[0,1]
	v_pk_fma_f32 v[24:25], v[10:11], v[86:87], v[24:25] op_sel:[1,0,0] op_sel_hi:[1,1,1]
	v_pk_fma_f32 v[24:25], v[8:9], v[88:89], v[24:25] op_sel:[0,0,0] op_sel_hi:[0,1,1]
	v_pk_fma_f32 v[24:25], v[8:9], v[90:91], v[24:25] op_sel:[1,0,0] op_sel_hi:[1,1,1]
	v_pk_fma_f32 v[16:17], v[92:93], v[156:157], v[10:11] op_sel:[0,1,0] op_sel_hi:[1,1,1]
	v_pk_fma_f32 v[18:19], v[94:95], v[156:157], v[8:9] op_sel:[0,1,0] op_sel_hi:[1,1,1]
	v_add_f32_dpp v15, v24, v24 row_ror:8 row_mask:0xf bank_mask:0xf bound_ctrl:1
	ds_read_b128 v[76:79], v48 offset:4096
	s_nop 0
	v_add_f32_dpp v15, v15, v15 row_ror:4 row_mask:0xf bank_mask:0xf bound_ctrl:1
	ds_read_b128 v[128:131], v48 offset:3328
	ds_read_b128 v[132:135], v48 offset:3584
	v_add_f32_dpp v15, v15, v15 row_ror:2 row_mask:0xf bank_mask:0xf bound_ctrl:1
	ds_read_b128 v[136:139], v48 offset:3840
	ds_read_b128 v[160:163], v49 offset:16
	v_add_f32_dpp v30, v15, v15 row_ror:1 row_mask:0xf bank_mask:0xf bound_ctrl:1
	s_waitcnt lgkmcnt(11)
	v_pk_fma_f32 v[10:11], v[96:97], v[30:31], v[16:17] op_sel_hi:[1,0,1] neg_lo:[0,1,0] neg_hi:[0,1,0]
	v_pk_fma_f32 v[8:9], v[98:99], v[30:31], v[18:19] op_sel_hi:[1,0,1] neg_lo:[0,1,0] neg_hi:[0,1,0]
	v_pk_mul_f32 v[26:27], v[10:11], v[100:101] op_sel:[0,0] op_sel_hi:[0,1]
	v_pk_fma_f32 v[26:27], v[10:11], v[102:103], v[26:27] op_sel:[1,0,0] op_sel_hi:[1,1,1]
	v_pk_fma_f32 v[26:27], v[8:9], v[104:105], v[26:27] op_sel:[0,0,0] op_sel_hi:[0,1,1]
	v_pk_fma_f32 v[26:27], v[8:9], v[106:107], v[26:27] op_sel:[1,0,0] op_sel_hi:[1,1,1]
	v_pk_fma_f32 v[16:17], v[108:109], v[158:159], v[10:11] op_sel_hi:[1,0,1]
	v_pk_fma_f32 v[18:19], v[110:111], v[158:159], v[8:9] op_sel_hi:[1,0,1]
	v_add_f32_dpp v15, v26, v26 row_ror:8 row_mask:0xf bank_mask:0xf bound_ctrl:1
	ds_read_b128 v[92:95], v48 offset:5120
	s_nop 0
	v_add_f32_dpp v15, v15, v15 row_ror:4 row_mask:0xf bank_mask:0xf bound_ctrl:1
	ds_read_b128 v[80:83], v48 offset:4352
	ds_read_b128 v[84:87], v48 offset:4608
	v_add_f32_dpp v15, v15, v15 row_ror:2 row_mask:0xf bank_mask:0xf bound_ctrl:1
	ds_read_b128 v[88:91], v48 offset:4864
	ds_write2st64_b32 v50, v25, v27 offset0:0 offset1:4
	v_add_f32_dpp v30, v15, v15 row_ror:1 row_mask:0xf bank_mask:0xf bound_ctrl:1
	s_waitcnt lgkmcnt(10)
	v_pk_fma_f32 v[10:11], v[112:113], v[30:31], v[16:17] op_sel_hi:[1,0,1] neg_lo:[0,1,0] neg_hi:[0,1,0]
	v_pk_fma_f32 v[8:9], v[114:115], v[30:31], v[18:19] op_sel_hi:[1,0,1] neg_lo:[0,1,0] neg_hi:[0,1,0]
	v_pk_mul_f32 v[24:25], v[10:11], v[116:117] op_sel:[0,0] op_sel_hi:[0,1]
	v_pk_fma_f32 v[24:25], v[10:11], v[118:119], v[24:25] op_sel:[1,0,0] op_sel_hi:[1,1,1]
	v_pk_fma_f32 v[24:25], v[8:9], v[120:121], v[24:25] op_sel:[0,0,0] op_sel_hi:[0,1,1]
	v_pk_fma_f32 v[24:25], v[8:9], v[122:123], v[24:25] op_sel:[1,0,0] op_sel_hi:[1,1,1]
	v_pk_fma_f32 v[16:17], v[124:125], v[158:159], v[10:11] op_sel:[0,1,0] op_sel_hi:[1,1,1]
	v_pk_fma_f32 v[18:19], v[126:127], v[158:159], v[8:9] op_sel:[0,1,0] op_sel_hi:[1,1,1]
	v_add_f32_dpp v15, v24, v24 row_ror:8 row_mask:0xf bank_mask:0xf bound_ctrl:1
	ds_read_b128 v[108:111], v48 offset:6144
	s_nop 0
	v_add_f32_dpp v15, v15, v15 row_ror:4 row_mask:0xf bank_mask:0xf bound_ctrl:1
	ds_read_b128 v[96:99], v48 offset:5376
	ds_read_b128 v[100:103], v48 offset:5632
	v_add_f32_dpp v15, v15, v15 row_ror:2 row_mask:0xf bank_mask:0xf bound_ctrl:1
	ds_read_b128 v[104:107], v48 offset:5888
	s_nop 0
	v_add_f32_dpp v30, v15, v15 row_ror:1 row_mask:0xf bank_mask:0xf bound_ctrl:1
	s_waitcnt lgkmcnt(9)
	v_pk_fma_f32 v[10:11], v[128:129], v[30:31], v[16:17] op_sel_hi:[1,0,1] neg_lo:[0,1,0] neg_hi:[0,1,0]
	v_pk_fma_f32 v[8:9], v[130:131], v[30:31], v[18:19] op_sel_hi:[1,0,1] neg_lo:[0,1,0] neg_hi:[0,1,0]
	v_pk_mul_f32 v[26:27], v[10:11], v[132:133] op_sel:[0,0] op_sel_hi:[0,1]
	v_pk_fma_f32 v[26:27], v[10:11], v[134:135], v[26:27] op_sel:[1,0,0] op_sel_hi:[1,1,1]
	v_pk_fma_f32 v[26:27], v[8:9], v[136:137], v[26:27] op_sel:[0,0,0] op_sel_hi:[0,1,1]
	v_pk_fma_f32 v[26:27], v[8:9], v[138:139], v[26:27] op_sel:[1,0,0] op_sel_hi:[1,1,1]
	v_pk_fma_f32 v[16:17], v[76:77], v[160:161], v[10:11] op_sel_hi:[1,0,1]
	v_pk_fma_f32 v[18:19], v[78:79], v[160:161], v[8:9] op_sel_hi:[1,0,1]
	v_add_f32_dpp v15, v26, v26 row_ror:8 row_mask:0xf bank_mask:0xf bound_ctrl:1
	ds_read_b128 v[124:127], v48 offset:7168
	s_nop 0
	v_add_f32_dpp v15, v15, v15 row_ror:4 row_mask:0xf bank_mask:0xf bound_ctrl:1
	ds_read_b128 v[112:115], v48 offset:6400
	ds_read_b128 v[116:119], v48 offset:6656
	v_add_f32_dpp v15, v15, v15 row_ror:2 row_mask:0xf bank_mask:0xf bound_ctrl:1
	ds_read_b128 v[120:123], v48 offset:6912
	ds_write2st64_b32 v50, v25, v27 offset0:8 offset1:12
	v_add_f32_dpp v30, v15, v15 row_ror:1 row_mask:0xf bank_mask:0xf bound_ctrl:1
	s_waitcnt lgkmcnt(9)
	v_pk_fma_f32 v[10:11], v[80:81], v[30:31], v[16:17] op_sel_hi:[1,0,1] neg_lo:[0,1,0] neg_hi:[0,1,0]
	v_pk_fma_f32 v[8:9], v[82:83], v[30:31], v[18:19] op_sel_hi:[1,0,1] neg_lo:[0,1,0] neg_hi:[0,1,0]
	v_pk_mul_f32 v[24:25], v[10:11], v[84:85] op_sel:[0,0] op_sel_hi:[0,1]
	v_pk_fma_f32 v[24:25], v[10:11], v[86:87], v[24:25] op_sel:[1,0,0] op_sel_hi:[1,1,1]
	v_pk_fma_f32 v[24:25], v[8:9], v[88:89], v[24:25] op_sel:[0,0,0] op_sel_hi:[0,1,1]
	v_pk_fma_f32 v[24:25], v[8:9], v[90:91], v[24:25] op_sel:[1,0,0] op_sel_hi:[1,1,1]
	v_pk_fma_f32 v[16:17], v[92:93], v[160:161], v[10:11] op_sel:[0,1,0] op_sel_hi:[1,1,1]
	v_pk_fma_f32 v[18:19], v[94:95], v[160:161], v[8:9] op_sel:[0,1,0] op_sel_hi:[1,1,1]
	v_add_f32_dpp v15, v24, v24 row_ror:8 row_mask:0xf bank_mask:0xf bound_ctrl:1
	ds_read_b128 v[76:79], v48 offset:8192
	s_nop 0
	v_add_f32_dpp v15, v15, v15 row_ror:4 row_mask:0xf bank_mask:0xf bound_ctrl:1
	ds_read_b128 v[128:131], v48 offset:7424
	ds_read_b128 v[132:135], v48 offset:7680
	v_add_f32_dpp v15, v15, v15 row_ror:2 row_mask:0xf bank_mask:0xf bound_ctrl:1
	ds_read_b128 v[136:139], v48 offset:7936
	ds_read_b128 v[156:159], v49 offset:32
	v_add_f32_dpp v30, v15, v15 row_ror:1 row_mask:0xf bank_mask:0xf bound_ctrl:1
	s_waitcnt lgkmcnt(10)
	v_pk_fma_f32 v[10:11], v[96:97], v[30:31], v[16:17] op_sel_hi:[1,0,1] neg_lo:[0,1,0] neg_hi:[0,1,0]
	v_pk_fma_f32 v[8:9], v[98:99], v[30:31], v[18:19] op_sel_hi:[1,0,1] neg_lo:[0,1,0] neg_hi:[0,1,0]
	v_pk_mul_f32 v[26:27], v[10:11], v[100:101] op_sel:[0,0] op_sel_hi:[0,1]
	v_pk_fma_f32 v[26:27], v[10:11], v[102:103], v[26:27] op_sel:[1,0,0] op_sel_hi:[1,1,1]
	v_pk_fma_f32 v[26:27], v[8:9], v[104:105], v[26:27] op_sel:[0,0,0] op_sel_hi:[0,1,1]
	v_pk_fma_f32 v[26:27], v[8:9], v[106:107], v[26:27] op_sel:[1,0,0] op_sel_hi:[1,1,1]
	v_pk_fma_f32 v[16:17], v[108:109], v[162:163], v[10:11] op_sel_hi:[1,0,1]
	v_pk_fma_f32 v[18:19], v[110:111], v[162:163], v[8:9] op_sel_hi:[1,0,1]
	v_add_f32_dpp v15, v26, v26 row_ror:8 row_mask:0xf bank_mask:0xf bound_ctrl:1
	ds_read_b128 v[92:95], v48 offset:9216
	s_nop 0
	v_add_f32_dpp v15, v15, v15 row_ror:4 row_mask:0xf bank_mask:0xf bound_ctrl:1
	ds_read_b128 v[80:83], v48 offset:8448
	ds_read_b128 v[84:87], v48 offset:8704
	v_add_f32_dpp v15, v15, v15 row_ror:2 row_mask:0xf bank_mask:0xf bound_ctrl:1
	ds_read_b128 v[88:91], v48 offset:8960
	ds_write2st64_b32 v50, v25, v27 offset0:16 offset1:20
	v_add_f32_dpp v30, v15, v15 row_ror:1 row_mask:0xf bank_mask:0xf bound_ctrl:1
	s_waitcnt lgkmcnt(10)
	v_pk_fma_f32 v[10:11], v[112:113], v[30:31], v[16:17] op_sel_hi:[1,0,1] neg_lo:[0,1,0] neg_hi:[0,1,0]
	v_pk_fma_f32 v[8:9], v[114:115], v[30:31], v[18:19] op_sel_hi:[1,0,1] neg_lo:[0,1,0] neg_hi:[0,1,0]
	v_pk_mul_f32 v[24:25], v[10:11], v[116:117] op_sel:[0,0] op_sel_hi:[0,1]
	v_pk_fma_f32 v[24:25], v[10:11], v[118:119], v[24:25] op_sel:[1,0,0] op_sel_hi:[1,1,1]
	v_pk_fma_f32 v[24:25], v[8:9], v[120:121], v[24:25] op_sel:[0,0,0] op_sel_hi:[0,1,1]
	v_pk_fma_f32 v[24:25], v[8:9], v[122:123], v[24:25] op_sel:[1,0,0] op_sel_hi:[1,1,1]
	v_pk_fma_f32 v[16:17], v[124:125], v[162:163], v[10:11] op_sel:[0,1,0] op_sel_hi:[1,1,1]
	v_pk_fma_f32 v[18:19], v[126:127], v[162:163], v[8:9] op_sel:[0,1,0] op_sel_hi:[1,1,1]
	v_add_f32_dpp v15, v24, v24 row_ror:8 row_mask:0xf bank_mask:0xf bound_ctrl:1
	ds_read_b128 v[108:111], v48 offset:10240
	s_nop 0
	v_add_f32_dpp v15, v15, v15 row_ror:4 row_mask:0xf bank_mask:0xf bound_ctrl:1
	ds_read_b128 v[96:99], v48 offset:9472
	ds_read_b128 v[100:103], v48 offset:9728
	v_add_f32_dpp v15, v15, v15 row_ror:2 row_mask:0xf bank_mask:0xf bound_ctrl:1
	ds_read_b128 v[104:107], v48 offset:9984
	s_nop 0
	v_add_f32_dpp v30, v15, v15 row_ror:1 row_mask:0xf bank_mask:0xf bound_ctrl:1
	s_waitcnt lgkmcnt(9)
	v_pk_fma_f32 v[10:11], v[128:129], v[30:31], v[16:17] op_sel_hi:[1,0,1] neg_lo:[0,1,0] neg_hi:[0,1,0]
	v_pk_fma_f32 v[8:9], v[130:131], v[30:31], v[18:19] op_sel_hi:[1,0,1] neg_lo:[0,1,0] neg_hi:[0,1,0]
	v_pk_mul_f32 v[26:27], v[10:11], v[132:133] op_sel:[0,0] op_sel_hi:[0,1]
	v_pk_fma_f32 v[26:27], v[10:11], v[134:135], v[26:27] op_sel:[1,0,0] op_sel_hi:[1,1,1]
	v_pk_fma_f32 v[26:27], v[8:9], v[136:137], v[26:27] op_sel:[0,0,0] op_sel_hi:[0,1,1]
	v_pk_fma_f32 v[26:27], v[8:9], v[138:139], v[26:27] op_sel:[1,0,0] op_sel_hi:[1,1,1]
	v_pk_fma_f32 v[16:17], v[76:77], v[156:157], v[10:11] op_sel_hi:[1,0,1]
	v_pk_fma_f32 v[18:19], v[78:79], v[156:157], v[8:9] op_sel_hi:[1,0,1]
	v_add_f32_dpp v15, v26, v26 row_ror:8 row_mask:0xf bank_mask:0xf bound_ctrl:1
	ds_read_b128 v[124:127], v48 offset:11264
	s_nop 0
	v_add_f32_dpp v15, v15, v15 row_ror:4 row_mask:0xf bank_mask:0xf bound_ctrl:1
	ds_read_b128 v[112:115], v48 offset:10496
	ds_read_b128 v[116:119], v48 offset:10752
	v_add_f32_dpp v15, v15, v15 row_ror:2 row_mask:0xf bank_mask:0xf bound_ctrl:1
	ds_read_b128 v[120:123], v48 offset:11008
	ds_write2st64_b32 v50, v25, v27 offset0:24 offset1:28
	v_add_f32_dpp v30, v15, v15 row_ror:1 row_mask:0xf bank_mask:0xf bound_ctrl:1
	s_waitcnt lgkmcnt(9)
	v_pk_fma_f32 v[10:11], v[80:81], v[30:31], v[16:17] op_sel_hi:[1,0,1] neg_lo:[0,1,0] neg_hi:[0,1,0]
	v_pk_fma_f32 v[8:9], v[82:83], v[30:31], v[18:19] op_sel_hi:[1,0,1] neg_lo:[0,1,0] neg_hi:[0,1,0]
	v_pk_mul_f32 v[24:25], v[10:11], v[84:85] op_sel:[0,0] op_sel_hi:[0,1]
	v_pk_fma_f32 v[24:25], v[10:11], v[86:87], v[24:25] op_sel:[1,0,0] op_sel_hi:[1,1,1]
	v_pk_fma_f32 v[24:25], v[8:9], v[88:89], v[24:25] op_sel:[0,0,0] op_sel_hi:[0,1,1]
	v_pk_fma_f32 v[24:25], v[8:9], v[90:91], v[24:25] op_sel:[1,0,0] op_sel_hi:[1,1,1]
	v_pk_fma_f32 v[16:17], v[92:93], v[156:157], v[10:11] op_sel:[0,1,0] op_sel_hi:[1,1,1]
	v_pk_fma_f32 v[18:19], v[94:95], v[156:157], v[8:9] op_sel:[0,1,0] op_sel_hi:[1,1,1]
	v_add_f32_dpp v15, v24, v24 row_ror:8 row_mask:0xf bank_mask:0xf bound_ctrl:1
	ds_read_b128 v[76:79], v48 offset:12288
	s_nop 0
	v_add_f32_dpp v15, v15, v15 row_ror:4 row_mask:0xf bank_mask:0xf bound_ctrl:1
	ds_read_b128 v[128:131], v48 offset:11520
	ds_read_b128 v[132:135], v48 offset:11776
	v_add_f32_dpp v15, v15, v15 row_ror:2 row_mask:0xf bank_mask:0xf bound_ctrl:1
	ds_read_b128 v[136:139], v48 offset:12032
	ds_read_b128 v[160:163], v49 offset:48
	v_add_f32_dpp v30, v15, v15 row_ror:1 row_mask:0xf bank_mask:0xf bound_ctrl:1
	s_waitcnt lgkmcnt(10)
	v_pk_fma_f32 v[10:11], v[96:97], v[30:31], v[16:17] op_sel_hi:[1,0,1] neg_lo:[0,1,0] neg_hi:[0,1,0]
	v_pk_fma_f32 v[8:9], v[98:99], v[30:31], v[18:19] op_sel_hi:[1,0,1] neg_lo:[0,1,0] neg_hi:[0,1,0]
	v_pk_mul_f32 v[26:27], v[10:11], v[100:101] op_sel:[0,0] op_sel_hi:[0,1]
	v_pk_fma_f32 v[26:27], v[10:11], v[102:103], v[26:27] op_sel:[1,0,0] op_sel_hi:[1,1,1]
	v_pk_fma_f32 v[26:27], v[8:9], v[104:105], v[26:27] op_sel:[0,0,0] op_sel_hi:[0,1,1]
	v_pk_fma_f32 v[26:27], v[8:9], v[106:107], v[26:27] op_sel:[1,0,0] op_sel_hi:[1,1,1]
	v_pk_fma_f32 v[16:17], v[108:109], v[158:159], v[10:11] op_sel_hi:[1,0,1]
	v_pk_fma_f32 v[18:19], v[110:111], v[158:159], v[8:9] op_sel_hi:[1,0,1]
	v_add_f32_dpp v15, v26, v26 row_ror:8 row_mask:0xf bank_mask:0xf bound_ctrl:1
	ds_read_b128 v[92:95], v48 offset:13312
	s_nop 0
	v_add_f32_dpp v15, v15, v15 row_ror:4 row_mask:0xf bank_mask:0xf bound_ctrl:1
	ds_read_b128 v[80:83], v48 offset:12544
	ds_read_b128 v[84:87], v48 offset:12800
	v_add_f32_dpp v15, v15, v15 row_ror:2 row_mask:0xf bank_mask:0xf bound_ctrl:1
	ds_read_b128 v[88:91], v48 offset:13056
	ds_write2st64_b32 v50, v25, v27 offset0:32 offset1:36
	v_add_f32_dpp v30, v15, v15 row_ror:1 row_mask:0xf bank_mask:0xf bound_ctrl:1
	s_waitcnt lgkmcnt(10)
	v_pk_fma_f32 v[10:11], v[112:113], v[30:31], v[16:17] op_sel_hi:[1,0,1] neg_lo:[0,1,0] neg_hi:[0,1,0]
	v_pk_fma_f32 v[8:9], v[114:115], v[30:31], v[18:19] op_sel_hi:[1,0,1] neg_lo:[0,1,0] neg_hi:[0,1,0]
	v_pk_mul_f32 v[24:25], v[10:11], v[116:117] op_sel:[0,0] op_sel_hi:[0,1]
	v_pk_fma_f32 v[24:25], v[10:11], v[118:119], v[24:25] op_sel:[1,0,0] op_sel_hi:[1,1,1]
	v_pk_fma_f32 v[24:25], v[8:9], v[120:121], v[24:25] op_sel:[0,0,0] op_sel_hi:[0,1,1]
	v_pk_fma_f32 v[24:25], v[8:9], v[122:123], v[24:25] op_sel:[1,0,0] op_sel_hi:[1,1,1]
	v_pk_fma_f32 v[16:17], v[124:125], v[158:159], v[10:11] op_sel:[0,1,0] op_sel_hi:[1,1,1]
	v_pk_fma_f32 v[18:19], v[126:127], v[158:159], v[8:9] op_sel:[0,1,0] op_sel_hi:[1,1,1]
	v_add_f32_dpp v15, v24, v24 row_ror:8 row_mask:0xf bank_mask:0xf bound_ctrl:1
	ds_read_b128 v[108:111], v48 offset:14336
	s_nop 0
	v_add_f32_dpp v15, v15, v15 row_ror:4 row_mask:0xf bank_mask:0xf bound_ctrl:1
	ds_read_b128 v[96:99], v48 offset:13568
	ds_read_b128 v[100:103], v48 offset:13824
	v_add_f32_dpp v15, v15, v15 row_ror:2 row_mask:0xf bank_mask:0xf bound_ctrl:1
	ds_read_b128 v[104:107], v48 offset:14080
	s_nop 0
	v_add_f32_dpp v30, v15, v15 row_ror:1 row_mask:0xf bank_mask:0xf bound_ctrl:1
	s_waitcnt lgkmcnt(9)
	v_pk_fma_f32 v[10:11], v[128:129], v[30:31], v[16:17] op_sel_hi:[1,0,1] neg_lo:[0,1,0] neg_hi:[0,1,0]
	v_pk_fma_f32 v[8:9], v[130:131], v[30:31], v[18:19] op_sel_hi:[1,0,1] neg_lo:[0,1,0] neg_hi:[0,1,0]
	v_pk_mul_f32 v[26:27], v[10:11], v[132:133] op_sel:[0,0] op_sel_hi:[0,1]
	v_pk_fma_f32 v[26:27], v[10:11], v[134:135], v[26:27] op_sel:[1,0,0] op_sel_hi:[1,1,1]
	v_pk_fma_f32 v[26:27], v[8:9], v[136:137], v[26:27] op_sel:[0,0,0] op_sel_hi:[0,1,1]
	v_pk_fma_f32 v[26:27], v[8:9], v[138:139], v[26:27] op_sel:[1,0,0] op_sel_hi:[1,1,1]
	v_pk_fma_f32 v[16:17], v[76:77], v[160:161], v[10:11] op_sel_hi:[1,0,1]
	v_pk_fma_f32 v[18:19], v[78:79], v[160:161], v[8:9] op_sel_hi:[1,0,1]
	v_add_f32_dpp v15, v26, v26 row_ror:8 row_mask:0xf bank_mask:0xf bound_ctrl:1
	ds_read_b128 v[124:127], v48 offset:15360
	s_nop 0
	v_add_f32_dpp v15, v15, v15 row_ror:4 row_mask:0xf bank_mask:0xf bound_ctrl:1
	ds_read_b128 v[112:115], v48 offset:14592
	ds_read_b128 v[116:119], v48 offset:14848
	v_add_f32_dpp v15, v15, v15 row_ror:2 row_mask:0xf bank_mask:0xf bound_ctrl:1
	ds_read_b128 v[120:123], v48 offset:15104
	ds_write2st64_b32 v50, v25, v27 offset0:40 offset1:44
	v_add_f32_dpp v30, v15, v15 row_ror:1 row_mask:0xf bank_mask:0xf bound_ctrl:1
	s_waitcnt lgkmcnt(9)
	v_pk_fma_f32 v[10:11], v[80:81], v[30:31], v[16:17] op_sel_hi:[1,0,1] neg_lo:[0,1,0] neg_hi:[0,1,0]
	v_pk_fma_f32 v[8:9], v[82:83], v[30:31], v[18:19] op_sel_hi:[1,0,1] neg_lo:[0,1,0] neg_hi:[0,1,0]
	v_pk_mul_f32 v[24:25], v[10:11], v[84:85] op_sel:[0,0] op_sel_hi:[0,1]
	v_pk_fma_f32 v[24:25], v[10:11], v[86:87], v[24:25] op_sel:[1,0,0] op_sel_hi:[1,1,1]
	v_pk_fma_f32 v[24:25], v[8:9], v[88:89], v[24:25] op_sel:[0,0,0] op_sel_hi:[0,1,1]
	v_pk_fma_f32 v[24:25], v[8:9], v[90:91], v[24:25] op_sel:[1,0,0] op_sel_hi:[1,1,1]
	v_pk_fma_f32 v[16:17], v[92:93], v[160:161], v[10:11] op_sel:[0,1,0] op_sel_hi:[1,1,1]
	v_pk_fma_f32 v[18:19], v[94:95], v[160:161], v[8:9] op_sel:[0,1,0] op_sel_hi:[1,1,1]
	v_add_f32_dpp v15, v24, v24 row_ror:8 row_mask:0xf bank_mask:0xf bound_ctrl:1
	ds_read_b128 v[76:79], v48 offset:16384
	s_nop 0
	v_add_f32_dpp v15, v15, v15 row_ror:4 row_mask:0xf bank_mask:0xf bound_ctrl:1
	ds_read_b128 v[128:131], v48 offset:15616
	ds_read_b128 v[132:135], v48 offset:15872
	v_add_f32_dpp v15, v15, v15 row_ror:2 row_mask:0xf bank_mask:0xf bound_ctrl:1
	ds_read_b128 v[136:139], v48 offset:16128
	ds_read_b128 v[156:159], v49 offset:64
	v_add_f32_dpp v30, v15, v15 row_ror:1 row_mask:0xf bank_mask:0xf bound_ctrl:1
	s_waitcnt lgkmcnt(10)
	v_pk_fma_f32 v[10:11], v[96:97], v[30:31], v[16:17] op_sel_hi:[1,0,1] neg_lo:[0,1,0] neg_hi:[0,1,0]
	v_pk_fma_f32 v[8:9], v[98:99], v[30:31], v[18:19] op_sel_hi:[1,0,1] neg_lo:[0,1,0] neg_hi:[0,1,0]
	v_pk_mul_f32 v[26:27], v[10:11], v[100:101] op_sel:[0,0] op_sel_hi:[0,1]
	v_pk_fma_f32 v[26:27], v[10:11], v[102:103], v[26:27] op_sel:[1,0,0] op_sel_hi:[1,1,1]
	v_pk_fma_f32 v[26:27], v[8:9], v[104:105], v[26:27] op_sel:[0,0,0] op_sel_hi:[0,1,1]
	v_pk_fma_f32 v[26:27], v[8:9], v[106:107], v[26:27] op_sel:[1,0,0] op_sel_hi:[1,1,1]
	v_pk_fma_f32 v[16:17], v[108:109], v[162:163], v[10:11] op_sel_hi:[1,0,1]
	v_pk_fma_f32 v[18:19], v[110:111], v[162:163], v[8:9] op_sel_hi:[1,0,1]
	v_add_f32_dpp v15, v26, v26 row_ror:8 row_mask:0xf bank_mask:0xf bound_ctrl:1
	ds_read_b128 v[92:95], v48 offset:17408
	s_nop 0
	v_add_f32_dpp v15, v15, v15 row_ror:4 row_mask:0xf bank_mask:0xf bound_ctrl:1
	ds_read_b128 v[80:83], v48 offset:16640
	ds_read_b128 v[84:87], v48 offset:16896
	v_add_f32_dpp v15, v15, v15 row_ror:2 row_mask:0xf bank_mask:0xf bound_ctrl:1
	ds_read_b128 v[88:91], v48 offset:17152
	ds_write2st64_b32 v50, v25, v27 offset0:48 offset1:52
	v_add_f32_dpp v30, v15, v15 row_ror:1 row_mask:0xf bank_mask:0xf bound_ctrl:1
	s_waitcnt lgkmcnt(10)
	v_pk_fma_f32 v[10:11], v[112:113], v[30:31], v[16:17] op_sel_hi:[1,0,1] neg_lo:[0,1,0] neg_hi:[0,1,0]
	v_pk_fma_f32 v[8:9], v[114:115], v[30:31], v[18:19] op_sel_hi:[1,0,1] neg_lo:[0,1,0] neg_hi:[0,1,0]
	v_pk_mul_f32 v[24:25], v[10:11], v[116:117] op_sel:[0,0] op_sel_hi:[0,1]
	v_pk_fma_f32 v[24:25], v[10:11], v[118:119], v[24:25] op_sel:[1,0,0] op_sel_hi:[1,1,1]
	v_pk_fma_f32 v[24:25], v[8:9], v[120:121], v[24:25] op_sel:[0,0,0] op_sel_hi:[0,1,1]
	v_pk_fma_f32 v[24:25], v[8:9], v[122:123], v[24:25] op_sel:[1,0,0] op_sel_hi:[1,1,1]
	v_pk_fma_f32 v[16:17], v[124:125], v[162:163], v[10:11] op_sel:[0,1,0] op_sel_hi:[1,1,1]
	v_pk_fma_f32 v[18:19], v[126:127], v[162:163], v[8:9] op_sel:[0,1,0] op_sel_hi:[1,1,1]
	v_add_f32_dpp v15, v24, v24 row_ror:8 row_mask:0xf bank_mask:0xf bound_ctrl:1
	ds_read_b128 v[108:111], v48 offset:18432
	s_nop 0
	v_add_f32_dpp v15, v15, v15 row_ror:4 row_mask:0xf bank_mask:0xf bound_ctrl:1
	ds_read_b128 v[96:99], v48 offset:17664
	ds_read_b128 v[100:103], v48 offset:17920
	v_add_f32_dpp v15, v15, v15 row_ror:2 row_mask:0xf bank_mask:0xf bound_ctrl:1
	ds_read_b128 v[104:107], v48 offset:18176
	s_nop 0
	v_add_f32_dpp v30, v15, v15 row_ror:1 row_mask:0xf bank_mask:0xf bound_ctrl:1
	s_waitcnt lgkmcnt(9)
	v_pk_fma_f32 v[10:11], v[128:129], v[30:31], v[16:17] op_sel_hi:[1,0,1] neg_lo:[0,1,0] neg_hi:[0,1,0]
	v_pk_fma_f32 v[8:9], v[130:131], v[30:31], v[18:19] op_sel_hi:[1,0,1] neg_lo:[0,1,0] neg_hi:[0,1,0]
	v_pk_mul_f32 v[26:27], v[10:11], v[132:133] op_sel:[0,0] op_sel_hi:[0,1]
	v_pk_fma_f32 v[26:27], v[10:11], v[134:135], v[26:27] op_sel:[1,0,0] op_sel_hi:[1,1,1]
	v_pk_fma_f32 v[26:27], v[8:9], v[136:137], v[26:27] op_sel:[0,0,0] op_sel_hi:[0,1,1]
	v_pk_fma_f32 v[26:27], v[8:9], v[138:139], v[26:27] op_sel:[1,0,0] op_sel_hi:[1,1,1]
	v_pk_fma_f32 v[16:17], v[76:77], v[156:157], v[10:11] op_sel_hi:[1,0,1]
	v_pk_fma_f32 v[18:19], v[78:79], v[156:157], v[8:9] op_sel_hi:[1,0,1]
	v_add_f32_dpp v15, v26, v26 row_ror:8 row_mask:0xf bank_mask:0xf bound_ctrl:1
	ds_read_b128 v[124:127], v48 offset:19456
	s_nop 0
	v_add_f32_dpp v15, v15, v15 row_ror:4 row_mask:0xf bank_mask:0xf bound_ctrl:1
	ds_read_b128 v[112:115], v48 offset:18688
	ds_read_b128 v[116:119], v48 offset:18944
	v_add_f32_dpp v15, v15, v15 row_ror:2 row_mask:0xf bank_mask:0xf bound_ctrl:1
	ds_read_b128 v[120:123], v48 offset:19200
	ds_write2st64_b32 v50, v25, v27 offset0:56 offset1:60
	v_add_f32_dpp v30, v15, v15 row_ror:1 row_mask:0xf bank_mask:0xf bound_ctrl:1
	s_waitcnt lgkmcnt(9)
	v_pk_fma_f32 v[10:11], v[80:81], v[30:31], v[16:17] op_sel_hi:[1,0,1] neg_lo:[0,1,0] neg_hi:[0,1,0]
	v_pk_fma_f32 v[8:9], v[82:83], v[30:31], v[18:19] op_sel_hi:[1,0,1] neg_lo:[0,1,0] neg_hi:[0,1,0]
	v_pk_mul_f32 v[24:25], v[10:11], v[84:85] op_sel:[0,0] op_sel_hi:[0,1]
	v_pk_fma_f32 v[24:25], v[10:11], v[86:87], v[24:25] op_sel:[1,0,0] op_sel_hi:[1,1,1]
	v_pk_fma_f32 v[24:25], v[8:9], v[88:89], v[24:25] op_sel:[0,0,0] op_sel_hi:[0,1,1]
	v_pk_fma_f32 v[24:25], v[8:9], v[90:91], v[24:25] op_sel:[1,0,0] op_sel_hi:[1,1,1]
	v_pk_fma_f32 v[16:17], v[92:93], v[156:157], v[10:11] op_sel:[0,1,0] op_sel_hi:[1,1,1]
	v_pk_fma_f32 v[18:19], v[94:95], v[156:157], v[8:9] op_sel:[0,1,0] op_sel_hi:[1,1,1]
	v_add_f32_dpp v15, v24, v24 row_ror:8 row_mask:0xf bank_mask:0xf bound_ctrl:1
	ds_read_b128 v[76:79], v48 offset:20480
	s_nop 0
	v_add_f32_dpp v15, v15, v15 row_ror:4 row_mask:0xf bank_mask:0xf bound_ctrl:1
	ds_read_b128 v[128:131], v48 offset:19712
	ds_read_b128 v[132:135], v48 offset:19968
	v_add_f32_dpp v15, v15, v15 row_ror:2 row_mask:0xf bank_mask:0xf bound_ctrl:1
	ds_read_b128 v[136:139], v48 offset:20224
	ds_read_b128 v[160:163], v49 offset:80
	v_add_f32_dpp v30, v15, v15 row_ror:1 row_mask:0xf bank_mask:0xf bound_ctrl:1
	s_waitcnt lgkmcnt(10)
	v_pk_fma_f32 v[10:11], v[96:97], v[30:31], v[16:17] op_sel_hi:[1,0,1] neg_lo:[0,1,0] neg_hi:[0,1,0]
	v_pk_fma_f32 v[8:9], v[98:99], v[30:31], v[18:19] op_sel_hi:[1,0,1] neg_lo:[0,1,0] neg_hi:[0,1,0]
	v_pk_mul_f32 v[26:27], v[10:11], v[100:101] op_sel:[0,0] op_sel_hi:[0,1]
	v_pk_fma_f32 v[26:27], v[10:11], v[102:103], v[26:27] op_sel:[1,0,0] op_sel_hi:[1,1,1]
	v_pk_fma_f32 v[26:27], v[8:9], v[104:105], v[26:27] op_sel:[0,0,0] op_sel_hi:[0,1,1]
	v_pk_fma_f32 v[26:27], v[8:9], v[106:107], v[26:27] op_sel:[1,0,0] op_sel_hi:[1,1,1]
	v_pk_fma_f32 v[16:17], v[108:109], v[158:159], v[10:11] op_sel_hi:[1,0,1]
	v_pk_fma_f32 v[18:19], v[110:111], v[158:159], v[8:9] op_sel_hi:[1,0,1]
	v_add_f32_dpp v15, v26, v26 row_ror:8 row_mask:0xf bank_mask:0xf bound_ctrl:1
	ds_read_b128 v[92:95], v48 offset:21504
	s_nop 0
	v_add_f32_dpp v15, v15, v15 row_ror:4 row_mask:0xf bank_mask:0xf bound_ctrl:1
	ds_read_b128 v[80:83], v48 offset:20736
	ds_read_b128 v[84:87], v48 offset:20992
	v_add_f32_dpp v15, v15, v15 row_ror:2 row_mask:0xf bank_mask:0xf bound_ctrl:1
	ds_read_b128 v[88:91], v48 offset:21248
	ds_write2st64_b32 v50, v25, v27 offset0:64 offset1:68
	v_add_f32_dpp v30, v15, v15 row_ror:1 row_mask:0xf bank_mask:0xf bound_ctrl:1
	s_waitcnt lgkmcnt(10)
	v_pk_fma_f32 v[10:11], v[112:113], v[30:31], v[16:17] op_sel_hi:[1,0,1] neg_lo:[0,1,0] neg_hi:[0,1,0]
	v_pk_fma_f32 v[8:9], v[114:115], v[30:31], v[18:19] op_sel_hi:[1,0,1] neg_lo:[0,1,0] neg_hi:[0,1,0]
	v_pk_mul_f32 v[24:25], v[10:11], v[116:117] op_sel:[0,0] op_sel_hi:[0,1]
	v_pk_fma_f32 v[24:25], v[10:11], v[118:119], v[24:25] op_sel:[1,0,0] op_sel_hi:[1,1,1]
	v_pk_fma_f32 v[24:25], v[8:9], v[120:121], v[24:25] op_sel:[0,0,0] op_sel_hi:[0,1,1]
	v_pk_fma_f32 v[24:25], v[8:9], v[122:123], v[24:25] op_sel:[1,0,0] op_sel_hi:[1,1,1]
	v_pk_fma_f32 v[16:17], v[124:125], v[158:159], v[10:11] op_sel:[0,1,0] op_sel_hi:[1,1,1]
	v_pk_fma_f32 v[18:19], v[126:127], v[158:159], v[8:9] op_sel:[0,1,0] op_sel_hi:[1,1,1]
	v_add_f32_dpp v15, v24, v24 row_ror:8 row_mask:0xf bank_mask:0xf bound_ctrl:1
	ds_read_b128 v[108:111], v48 offset:22528
	s_nop 0
	v_add_f32_dpp v15, v15, v15 row_ror:4 row_mask:0xf bank_mask:0xf bound_ctrl:1
	ds_read_b128 v[96:99], v48 offset:21760
	ds_read_b128 v[100:103], v48 offset:22016
	v_add_f32_dpp v15, v15, v15 row_ror:2 row_mask:0xf bank_mask:0xf bound_ctrl:1
	ds_read_b128 v[104:107], v48 offset:22272
	s_nop 0
	v_add_f32_dpp v30, v15, v15 row_ror:1 row_mask:0xf bank_mask:0xf bound_ctrl:1
	s_waitcnt lgkmcnt(9)
	v_pk_fma_f32 v[10:11], v[128:129], v[30:31], v[16:17] op_sel_hi:[1,0,1] neg_lo:[0,1,0] neg_hi:[0,1,0]
	v_pk_fma_f32 v[8:9], v[130:131], v[30:31], v[18:19] op_sel_hi:[1,0,1] neg_lo:[0,1,0] neg_hi:[0,1,0]
	v_pk_mul_f32 v[26:27], v[10:11], v[132:133] op_sel:[0,0] op_sel_hi:[0,1]
	v_pk_fma_f32 v[26:27], v[10:11], v[134:135], v[26:27] op_sel:[1,0,0] op_sel_hi:[1,1,1]
	v_pk_fma_f32 v[26:27], v[8:9], v[136:137], v[26:27] op_sel:[0,0,0] op_sel_hi:[0,1,1]
	v_pk_fma_f32 v[26:27], v[8:9], v[138:139], v[26:27] op_sel:[1,0,0] op_sel_hi:[1,1,1]
	v_pk_fma_f32 v[16:17], v[76:77], v[160:161], v[10:11] op_sel_hi:[1,0,1]
	v_pk_fma_f32 v[18:19], v[78:79], v[160:161], v[8:9] op_sel_hi:[1,0,1]
	v_add_f32_dpp v15, v26, v26 row_ror:8 row_mask:0xf bank_mask:0xf bound_ctrl:1
	ds_read_b128 v[124:127], v48 offset:23552
	s_nop 0
	v_add_f32_dpp v15, v15, v15 row_ror:4 row_mask:0xf bank_mask:0xf bound_ctrl:1
	ds_read_b128 v[112:115], v48 offset:22784
	ds_read_b128 v[116:119], v48 offset:23040
	v_add_f32_dpp v15, v15, v15 row_ror:2 row_mask:0xf bank_mask:0xf bound_ctrl:1
	ds_read_b128 v[120:123], v48 offset:23296
	ds_write2st64_b32 v50, v25, v27 offset0:72 offset1:76
	v_add_f32_dpp v30, v15, v15 row_ror:1 row_mask:0xf bank_mask:0xf bound_ctrl:1
	s_waitcnt lgkmcnt(9)
	v_pk_fma_f32 v[10:11], v[80:81], v[30:31], v[16:17] op_sel_hi:[1,0,1] neg_lo:[0,1,0] neg_hi:[0,1,0]
	v_pk_fma_f32 v[8:9], v[82:83], v[30:31], v[18:19] op_sel_hi:[1,0,1] neg_lo:[0,1,0] neg_hi:[0,1,0]
	v_pk_mul_f32 v[24:25], v[10:11], v[84:85] op_sel:[0,0] op_sel_hi:[0,1]
	v_pk_fma_f32 v[24:25], v[10:11], v[86:87], v[24:25] op_sel:[1,0,0] op_sel_hi:[1,1,1]
	v_pk_fma_f32 v[24:25], v[8:9], v[88:89], v[24:25] op_sel:[0,0,0] op_sel_hi:[0,1,1]
	v_pk_fma_f32 v[24:25], v[8:9], v[90:91], v[24:25] op_sel:[1,0,0] op_sel_hi:[1,1,1]
	v_pk_fma_f32 v[16:17], v[92:93], v[160:161], v[10:11] op_sel:[0,1,0] op_sel_hi:[1,1,1]
	v_pk_fma_f32 v[18:19], v[94:95], v[160:161], v[8:9] op_sel:[0,1,0] op_sel_hi:[1,1,1]
	v_add_f32_dpp v15, v24, v24 row_ror:8 row_mask:0xf bank_mask:0xf bound_ctrl:1
	ds_read_b128 v[76:79], v48 offset:24576
	s_nop 0
	v_add_f32_dpp v15, v15, v15 row_ror:4 row_mask:0xf bank_mask:0xf bound_ctrl:1
	ds_read_b128 v[128:131], v48 offset:23808
	ds_read_b128 v[132:135], v48 offset:24064
	v_add_f32_dpp v15, v15, v15 row_ror:2 row_mask:0xf bank_mask:0xf bound_ctrl:1
	ds_read_b128 v[136:139], v48 offset:24320
	ds_read_b128 v[156:159], v49 offset:96
	v_add_f32_dpp v30, v15, v15 row_ror:1 row_mask:0xf bank_mask:0xf bound_ctrl:1
	s_waitcnt lgkmcnt(10)
	v_pk_fma_f32 v[10:11], v[96:97], v[30:31], v[16:17] op_sel_hi:[1,0,1] neg_lo:[0,1,0] neg_hi:[0,1,0]
	v_pk_fma_f32 v[8:9], v[98:99], v[30:31], v[18:19] op_sel_hi:[1,0,1] neg_lo:[0,1,0] neg_hi:[0,1,0]
	v_pk_mul_f32 v[26:27], v[10:11], v[100:101] op_sel:[0,0] op_sel_hi:[0,1]
	v_pk_fma_f32 v[26:27], v[10:11], v[102:103], v[26:27] op_sel:[1,0,0] op_sel_hi:[1,1,1]
	v_pk_fma_f32 v[26:27], v[8:9], v[104:105], v[26:27] op_sel:[0,0,0] op_sel_hi:[0,1,1]
	v_pk_fma_f32 v[26:27], v[8:9], v[106:107], v[26:27] op_sel:[1,0,0] op_sel_hi:[1,1,1]
	v_pk_fma_f32 v[16:17], v[108:109], v[162:163], v[10:11] op_sel_hi:[1,0,1]
	v_pk_fma_f32 v[18:19], v[110:111], v[162:163], v[8:9] op_sel_hi:[1,0,1]
	v_add_f32_dpp v15, v26, v26 row_ror:8 row_mask:0xf bank_mask:0xf bound_ctrl:1
	ds_read_b128 v[92:95], v48 offset:25600
	s_nop 0
	v_add_f32_dpp v15, v15, v15 row_ror:4 row_mask:0xf bank_mask:0xf bound_ctrl:1
	ds_read_b128 v[80:83], v48 offset:24832
	ds_read_b128 v[84:87], v48 offset:25088
	v_add_f32_dpp v15, v15, v15 row_ror:2 row_mask:0xf bank_mask:0xf bound_ctrl:1
	ds_read_b128 v[88:91], v48 offset:25344
	ds_write2st64_b32 v50, v25, v27 offset0:80 offset1:84
	v_add_f32_dpp v30, v15, v15 row_ror:1 row_mask:0xf bank_mask:0xf bound_ctrl:1
	s_waitcnt lgkmcnt(10)
	v_pk_fma_f32 v[10:11], v[112:113], v[30:31], v[16:17] op_sel_hi:[1,0,1] neg_lo:[0,1,0] neg_hi:[0,1,0]
	v_pk_fma_f32 v[8:9], v[114:115], v[30:31], v[18:19] op_sel_hi:[1,0,1] neg_lo:[0,1,0] neg_hi:[0,1,0]
	v_pk_mul_f32 v[24:25], v[10:11], v[116:117] op_sel:[0,0] op_sel_hi:[0,1]
	v_pk_fma_f32 v[24:25], v[10:11], v[118:119], v[24:25] op_sel:[1,0,0] op_sel_hi:[1,1,1]
	v_pk_fma_f32 v[24:25], v[8:9], v[120:121], v[24:25] op_sel:[0,0,0] op_sel_hi:[0,1,1]
	v_pk_fma_f32 v[24:25], v[8:9], v[122:123], v[24:25] op_sel:[1,0,0] op_sel_hi:[1,1,1]
	v_pk_fma_f32 v[16:17], v[124:125], v[162:163], v[10:11] op_sel:[0,1,0] op_sel_hi:[1,1,1]
	v_pk_fma_f32 v[18:19], v[126:127], v[162:163], v[8:9] op_sel:[0,1,0] op_sel_hi:[1,1,1]
	v_add_f32_dpp v15, v24, v24 row_ror:8 row_mask:0xf bank_mask:0xf bound_ctrl:1
	ds_read_b128 v[108:111], v48 offset:26624
	s_nop 0
	v_add_f32_dpp v15, v15, v15 row_ror:4 row_mask:0xf bank_mask:0xf bound_ctrl:1
	ds_read_b128 v[96:99], v48 offset:25856
	ds_read_b128 v[100:103], v48 offset:26112
	v_add_f32_dpp v15, v15, v15 row_ror:2 row_mask:0xf bank_mask:0xf bound_ctrl:1
	ds_read_b128 v[104:107], v48 offset:26368
	s_nop 0
	v_add_f32_dpp v30, v15, v15 row_ror:1 row_mask:0xf bank_mask:0xf bound_ctrl:1
	s_waitcnt lgkmcnt(9)
	v_pk_fma_f32 v[10:11], v[128:129], v[30:31], v[16:17] op_sel_hi:[1,0,1] neg_lo:[0,1,0] neg_hi:[0,1,0]
	v_pk_fma_f32 v[8:9], v[130:131], v[30:31], v[18:19] op_sel_hi:[1,0,1] neg_lo:[0,1,0] neg_hi:[0,1,0]
	v_pk_mul_f32 v[26:27], v[10:11], v[132:133] op_sel:[0,0] op_sel_hi:[0,1]
	v_pk_fma_f32 v[26:27], v[10:11], v[134:135], v[26:27] op_sel:[1,0,0] op_sel_hi:[1,1,1]
	v_pk_fma_f32 v[26:27], v[8:9], v[136:137], v[26:27] op_sel:[0,0,0] op_sel_hi:[0,1,1]
	v_pk_fma_f32 v[26:27], v[8:9], v[138:139], v[26:27] op_sel:[1,0,0] op_sel_hi:[1,1,1]
	v_pk_fma_f32 v[16:17], v[76:77], v[156:157], v[10:11] op_sel_hi:[1,0,1]
	v_pk_fma_f32 v[18:19], v[78:79], v[156:157], v[8:9] op_sel_hi:[1,0,1]
	v_add_f32_dpp v15, v26, v26 row_ror:8 row_mask:0xf bank_mask:0xf bound_ctrl:1
	ds_read_b128 v[124:127], v48 offset:27648
	s_nop 0
	v_add_f32_dpp v15, v15, v15 row_ror:4 row_mask:0xf bank_mask:0xf bound_ctrl:1
	ds_read_b128 v[112:115], v48 offset:26880
	ds_read_b128 v[116:119], v48 offset:27136
	v_add_f32_dpp v15, v15, v15 row_ror:2 row_mask:0xf bank_mask:0xf bound_ctrl:1
	ds_read_b128 v[120:123], v48 offset:27392
	ds_write2st64_b32 v50, v25, v27 offset0:88 offset1:92
	v_add_f32_dpp v30, v15, v15 row_ror:1 row_mask:0xf bank_mask:0xf bound_ctrl:1
	s_waitcnt lgkmcnt(9)
	v_pk_fma_f32 v[10:11], v[80:81], v[30:31], v[16:17] op_sel_hi:[1,0,1] neg_lo:[0,1,0] neg_hi:[0,1,0]
	v_pk_fma_f32 v[8:9], v[82:83], v[30:31], v[18:19] op_sel_hi:[1,0,1] neg_lo:[0,1,0] neg_hi:[0,1,0]
	v_pk_mul_f32 v[24:25], v[10:11], v[84:85] op_sel:[0,0] op_sel_hi:[0,1]
	v_pk_fma_f32 v[24:25], v[10:11], v[86:87], v[24:25] op_sel:[1,0,0] op_sel_hi:[1,1,1]
	v_pk_fma_f32 v[24:25], v[8:9], v[88:89], v[24:25] op_sel:[0,0,0] op_sel_hi:[0,1,1]
	v_pk_fma_f32 v[24:25], v[8:9], v[90:91], v[24:25] op_sel:[1,0,0] op_sel_hi:[1,1,1]
	v_pk_fma_f32 v[16:17], v[92:93], v[156:157], v[10:11] op_sel:[0,1,0] op_sel_hi:[1,1,1]
	v_pk_fma_f32 v[18:19], v[94:95], v[156:157], v[8:9] op_sel:[0,1,0] op_sel_hi:[1,1,1]
	v_add_f32_dpp v15, v24, v24 row_ror:8 row_mask:0xf bank_mask:0xf bound_ctrl:1
	ds_read_b128 v[76:79], v48 offset:28672
	s_nop 0
	v_add_f32_dpp v15, v15, v15 row_ror:4 row_mask:0xf bank_mask:0xf bound_ctrl:1
	ds_read_b128 v[128:131], v48 offset:27904
	ds_read_b128 v[132:135], v48 offset:28160
	v_add_f32_dpp v15, v15, v15 row_ror:2 row_mask:0xf bank_mask:0xf bound_ctrl:1
	ds_read_b128 v[136:139], v48 offset:28416
	ds_read_b128 v[160:163], v49 offset:112
	v_add_f32_dpp v30, v15, v15 row_ror:1 row_mask:0xf bank_mask:0xf bound_ctrl:1
	ds_read_b128 v[56:59], v52
	s_waitcnt lgkmcnt(10)
	v_pk_fma_f32 v[10:11], v[96:97], v[30:31], v[16:17] op_sel_hi:[1,0,1] neg_lo:[0,1,0] neg_hi:[0,1,0]
	v_pk_fma_f32 v[8:9], v[98:99], v[30:31], v[18:19] op_sel_hi:[1,0,1] neg_lo:[0,1,0] neg_hi:[0,1,0]
	v_pk_mul_f32 v[26:27], v[10:11], v[100:101] op_sel:[0,0] op_sel_hi:[0,1]
	v_pk_fma_f32 v[26:27], v[10:11], v[102:103], v[26:27] op_sel:[1,0,0] op_sel_hi:[1,1,1]
	v_pk_fma_f32 v[26:27], v[8:9], v[104:105], v[26:27] op_sel:[0,0,0] op_sel_hi:[0,1,1]
	v_pk_fma_f32 v[26:27], v[8:9], v[106:107], v[26:27] op_sel:[1,0,0] op_sel_hi:[1,1,1]
	v_pk_fma_f32 v[16:17], v[108:109], v[158:159], v[10:11] op_sel_hi:[1,0,1]
	v_pk_fma_f32 v[18:19], v[110:111], v[158:159], v[8:9] op_sel_hi:[1,0,1]
	v_add_f32_dpp v15, v26, v26 row_ror:8 row_mask:0xf bank_mask:0xf bound_ctrl:1
	ds_read_b128 v[92:95], v48 offset:29696
	s_nop 0
	v_add_f32_dpp v15, v15, v15 row_ror:4 row_mask:0xf bank_mask:0xf bound_ctrl:1
	ds_read_b128 v[80:83], v48 offset:28928
	ds_read_b128 v[84:87], v48 offset:29184
	v_add_f32_dpp v15, v15, v15 row_ror:2 row_mask:0xf bank_mask:0xf bound_ctrl:1
	ds_read_b128 v[88:91], v48 offset:29440
	ds_write2st64_b32 v50, v25, v27 offset0:96 offset1:100
	v_add_f32_dpp v30, v15, v15 row_ror:1 row_mask:0xf bank_mask:0xf bound_ctrl:1
	s_waitcnt lgkmcnt(5)
	v_min_u32_e32 v56, v56, v57
	v_min3_u32 v56, v56, v58, v59
	v_pk_fma_f32 v[10:11], v[112:113], v[30:31], v[16:17] op_sel_hi:[1,0,1] neg_lo:[0,1,0] neg_hi:[0,1,0]
	v_pk_fma_f32 v[8:9], v[114:115], v[30:31], v[18:19] op_sel_hi:[1,0,1] neg_lo:[0,1,0] neg_hi:[0,1,0]
	v_pk_mul_f32 v[24:25], v[10:11], v[116:117] op_sel:[0,0] op_sel_hi:[0,1]
	v_pk_fma_f32 v[24:25], v[10:11], v[118:119], v[24:25] op_sel:[1,0,0] op_sel_hi:[1,1,1]
	v_pk_fma_f32 v[24:25], v[8:9], v[120:121], v[24:25] op_sel:[0,0,0] op_sel_hi:[0,1,1]
	v_pk_fma_f32 v[24:25], v[8:9], v[122:123], v[24:25] op_sel:[1,0,0] op_sel_hi:[1,1,1]
	v_pk_fma_f32 v[16:17], v[124:125], v[158:159], v[10:11] op_sel:[0,1,0] op_sel_hi:[1,1,1]
	v_pk_fma_f32 v[18:19], v[126:127], v[158:159], v[8:9] op_sel:[0,1,0] op_sel_hi:[1,1,1]
	v_add_f32_dpp v15, v24, v24 row_ror:8 row_mask:0xf bank_mask:0xf bound_ctrl:1
	ds_read_b128 v[108:111], v48 offset:30720
	s_nop 0
	v_add_f32_dpp v15, v15, v15 row_ror:4 row_mask:0xf bank_mask:0xf bound_ctrl:1
	ds_read_b128 v[96:99], v48 offset:29952
	ds_read_b128 v[100:103], v48 offset:30208
	v_add_f32_dpp v15, v15, v15 row_ror:2 row_mask:0xf bank_mask:0xf bound_ctrl:1
	ds_read_b128 v[104:107], v48 offset:30464
	s_nop 0
	v_add_f32_dpp v30, v15, v15 row_ror:1 row_mask:0xf bank_mask:0xf bound_ctrl:1
	v_pk_fma_f32 v[10:11], v[128:129], v[30:31], v[16:17] op_sel_hi:[1,0,1] neg_lo:[0,1,0] neg_hi:[0,1,0]
	v_pk_fma_f32 v[8:9], v[130:131], v[30:31], v[18:19] op_sel_hi:[1,0,1] neg_lo:[0,1,0] neg_hi:[0,1,0]
	v_pk_mul_f32 v[26:27], v[10:11], v[132:133] op_sel:[0,0] op_sel_hi:[0,1]
	v_pk_fma_f32 v[26:27], v[10:11], v[134:135], v[26:27] op_sel:[1,0,0] op_sel_hi:[1,1,1]
	v_pk_fma_f32 v[26:27], v[8:9], v[136:137], v[26:27] op_sel:[0,0,0] op_sel_hi:[0,1,1]
	v_pk_fma_f32 v[26:27], v[8:9], v[138:139], v[26:27] op_sel:[1,0,0] op_sel_hi:[1,1,1]
	v_pk_fma_f32 v[16:17], v[76:77], v[160:161], v[10:11] op_sel_hi:[1,0,1]
	v_pk_fma_f32 v[18:19], v[78:79], v[160:161], v[8:9] op_sel_hi:[1,0,1]
	v_add_f32_dpp v15, v26, v26 row_ror:8 row_mask:0xf bank_mask:0xf bound_ctrl:1
	ds_read_b128 v[124:127], v48 offset:31744
	s_nop 0
	v_add_f32_dpp v15, v15, v15 row_ror:4 row_mask:0xf bank_mask:0xf bound_ctrl:1
	ds_read_b128 v[112:115], v48 offset:30976
	ds_read_b128 v[116:119], v48 offset:31232
	v_add_f32_dpp v15, v15, v15 row_ror:2 row_mask:0xf bank_mask:0xf bound_ctrl:1
	ds_read_b128 v[120:123], v48 offset:31488
	ds_read_b128 v[140:143], v48 offset:34560
	ds_write2st64_b32 v50, v25, v27 offset0:104 offset1:108
	v_add_f32_dpp v30, v15, v15 row_ror:1 row_mask:0xf bank_mask:0xf bound_ctrl:1
	v_readfirstlane_b32 s54, v56
	s_add_u32 s64, s6, 2
	s_cmp_lt_u32 s54, s64
	s_cbranch_scc1 .Lss_spin_1
.Lss_ok_1:
	s_waitcnt lgkmcnt(10)
	v_pk_fma_f32 v[10:11], v[80:81], v[30:31], v[16:17] op_sel_hi:[1,0,1] neg_lo:[0,1,0] neg_hi:[0,1,0]
	v_pk_fma_f32 v[8:9], v[82:83], v[30:31], v[18:19] op_sel_hi:[1,0,1] neg_lo:[0,1,0] neg_hi:[0,1,0]
	v_pk_mul_f32 v[24:25], v[10:11], v[84:85] op_sel:[0,0] op_sel_hi:[0,1]
	v_pk_fma_f32 v[24:25], v[10:11], v[86:87], v[24:25] op_sel:[1,0,0] op_sel_hi:[1,1,1]
	v_pk_fma_f32 v[24:25], v[8:9], v[88:89], v[24:25] op_sel:[0,0,0] op_sel_hi:[0,1,1]
	v_pk_fma_f32 v[24:25], v[8:9], v[90:91], v[24:25] op_sel:[1,0,0] op_sel_hi:[1,1,1]
	v_pk_fma_f32 v[16:17], v[92:93], v[160:161], v[10:11] op_sel:[0,1,0] op_sel_hi:[1,1,1]
	v_pk_fma_f32 v[18:19], v[94:95], v[160:161], v[8:9] op_sel:[0,1,0] op_sel_hi:[1,1,1]
	v_add_f32_dpp v15, v24, v24 row_ror:8 row_mask:0xf bank_mask:0xf bound_ctrl:1
	ds_read_b128 v[76:79], v34 offset:0
	s_nop 0
	v_add_f32_dpp v15, v15, v15 row_ror:4 row_mask:0xf bank_mask:0xf bound_ctrl:1
	ds_read_b128 v[128:131], v48 offset:32000
	ds_read_b128 v[132:135], v48 offset:32256
	v_add_f32_dpp v15, v15, v15 row_ror:2 row_mask:0xf bank_mask:0xf bound_ctrl:1
	ds_read_b128 v[136:139], v48 offset:32512
	s_nop 0
	v_add_f32_dpp v30, v15, v15 row_ror:1 row_mask:0xf bank_mask:0xf bound_ctrl:1
	s_waitcnt lgkmcnt(10)
	v_pk_fma_f32 v[10:11], v[96:97], v[30:31], v[16:17] op_sel_hi:[1,0,1] neg_lo:[0,1,0] neg_hi:[0,1,0]
	v_pk_fma_f32 v[8:9], v[98:99], v[30:31], v[18:19] op_sel_hi:[1,0,1] neg_lo:[0,1,0] neg_hi:[0,1,0]
	v_pk_mul_f32 v[26:27], v[10:11], v[100:101] op_sel:[0,0] op_sel_hi:[0,1]
	v_pk_fma_f32 v[26:27], v[10:11], v[102:103], v[26:27] op_sel:[1,0,0] op_sel_hi:[1,1,1]
	v_pk_fma_f32 v[26:27], v[8:9], v[104:105], v[26:27] op_sel:[0,0,0] op_sel_hi:[0,1,1]
	v_pk_fma_f32 v[26:27], v[8:9], v[106:107], v[26:27] op_sel:[1,0,0] op_sel_hi:[1,1,1]
	v_pk_fma_f32 v[16:17], v[108:109], v[162:163], v[10:11] op_sel_hi:[1,0,1]
	v_pk_fma_f32 v[18:19], v[110:111], v[162:163], v[8:9] op_sel_hi:[1,0,1]
	v_add_f32_dpp v15, v26, v26 row_ror:8 row_mask:0xf bank_mask:0xf bound_ctrl:1
	ds_read_b128 v[92:95], v34 offset:1024
	s_nop 0
	v_add_f32_dpp v15, v15, v15 row_ror:4 row_mask:0xf bank_mask:0xf bound_ctrl:1
	ds_read_b128 v[80:83], v34 offset:256
	ds_read_b128 v[84:87], v34 offset:512
	v_add_f32_dpp v15, v15, v15 row_ror:2 row_mask:0xf bank_mask:0xf bound_ctrl:1
	ds_read_b128 v[88:91], v34 offset:768
	ds_read_b128 v[144:147], v34 offset:32768
	ds_write2st64_b32 v50, v25, v27 offset0:112 offset1:116
	v_add_f32_dpp v30, v15, v15 row_ror:1 row_mask:0xf bank_mask:0xf bound_ctrl:1
	ds_read_b128 v[156:159], v35 offset:0
	s_waitcnt lgkmcnt(11)
	v_pk_fma_f32 v[10:11], v[112:113], v[30:31], v[16:17] op_sel_hi:[1,0,1] neg_lo:[0,1,0] neg_hi:[0,1,0]
	v_pk_fma_f32 v[8:9], v[114:115], v[30:31], v[18:19] op_sel_hi:[1,0,1] neg_lo:[0,1,0] neg_hi:[0,1,0]
	v_pk_mul_f32 v[24:25], v[10:11], v[116:117] op_sel:[0,0] op_sel_hi:[0,1]
	v_pk_fma_f32 v[24:25], v[10:11], v[118:119], v[24:25] op_sel:[1,0,0] op_sel_hi:[1,1,1]
	v_pk_fma_f32 v[24:25], v[8:9], v[120:121], v[24:25] op_sel:[0,0,0] op_sel_hi:[0,1,1]
	v_pk_fma_f32 v[24:25], v[8:9], v[122:123], v[24:25] op_sel:[1,0,0] op_sel_hi:[1,1,1]
	v_pk_fma_f32 v[16:17], v[124:125], v[162:163], v[10:11] op_sel:[0,1,0] op_sel_hi:[1,1,1]
	v_pk_fma_f32 v[18:19], v[126:127], v[162:163], v[8:9] op_sel:[0,1,0] op_sel_hi:[1,1,1]
	v_add_f32_dpp v15, v24, v24 row_ror:8 row_mask:0xf bank_mask:0xf bound_ctrl:1
	ds_read_b128 v[108:111], v34 offset:2048
	s_nop 0
	v_add_f32_dpp v15, v15, v15 row_ror:4 row_mask:0xf bank_mask:0xf bound_ctrl:1
	ds_read_b128 v[96:99], v34 offset:1280
	ds_read_b128 v[100:103], v34 offset:1536
	v_add_f32_dpp v15, v15, v15 row_ror:2 row_mask:0xf bank_mask:0xf bound_ctrl:1
	ds_read_b128 v[104:107], v34 offset:1792
	s_nop 0
	v_add_f32_dpp v30, v15, v15 row_ror:1 row_mask:0xf bank_mask:0xf bound_ctrl:1
	s_waitcnt lgkmcnt(11)
	v_pk_fma_f32 v[10:11], v[128:129], v[30:31], v[16:17] op_sel_hi:[1,0,1] neg_lo:[0,1,0] neg_hi:[0,1,0]
	v_pk_fma_f32 v[8:9], v[130:131], v[30:31], v[18:19] op_sel_hi:[1,0,1] neg_lo:[0,1,0] neg_hi:[0,1,0]
	v_pk_mul_f32 v[26:27], v[10:11], v[132:133] op_sel:[0,0] op_sel_hi:[0,1]
	v_pk_fma_f32 v[26:27], v[10:11], v[134:135], v[26:27] op_sel:[1,0,0] op_sel_hi:[1,1,1]
	v_pk_fma_f32 v[26:27], v[8:9], v[136:137], v[26:27] op_sel:[0,0,0] op_sel_hi:[0,1,1]
	v_pk_fma_f32 v[26:27], v[8:9], v[138:139], v[26:27] op_sel:[1,0,0] op_sel_hi:[1,1,1]
	ds_write2st64_b32 v50, v25, v27 offset0:120 offset1:124
	v_pk_mul_f32 v[10:11], v[10:11], v[140:141]
	v_pk_mul_f32 v[8:9], v[8:9], v[142:143]
	s_waitcnt lgkmcnt(7)
	v_pk_mul_f32 v[24:25], v[10:11], v[144:145]
	v_pk_fma_f32 v[24:25], v[8:9], v[146:147], v[24:25]
	v_add_f32_e32 v24, v24, v25
	s_waitcnt lgkmcnt(5)
	v_pk_fma_f32 v[16:17], v[76:77], v[156:157], v[10:11] op_sel_hi:[1,0,1]
	v_pk_fma_f32 v[18:19], v[78:79], v[156:157], v[8:9] op_sel_hi:[1,0,1]
	v_add_f32_dpp v15, v24, v24 row_ror:8 row_mask:0xf bank_mask:0xf bound_ctrl:1
	v_add_u32_e32 v51, 1, v51
	s_add_u32 s6, s6, 1
	v_add_f32_dpp v15, v15, v15 row_ror:4 row_mask:0xf bank_mask:0xf bound_ctrl:1
	ds_write_b32 v53, v51
	ds_read_b128 v[124:127], v34 offset:3072
	v_add_f32_dpp v15, v15, v15 row_ror:2 row_mask:0xf bank_mask:0xf bound_ctrl:1
	ds_read_b128 v[112:115], v34 offset:2304
	ds_read_b128 v[116:119], v34 offset:2560
	v_add_f32_dpp v30, v15, v15 row_ror:1 row_mask:0xf bank_mask:0xf bound_ctrl:1
	ds_read_b128 v[120:123], v34 offset:2816
	s_cmp_lt_u32 s6, 0x100
	s_cbranch_scc1 .Lsc_S_loop
	s_waitcnt lgkmcnt(0)
	s_branch .Lsc_item_end
	s_nop 0
	s_nop 0
	s_nop 0
	s_nop 0
	s_nop 0
	s_nop 0
	s_nop 0
	s_nop 0
	s_nop 0
	s_nop 0
	s_nop 0
	s_nop 0
	s_nop 0
	s_nop 0
	s_nop 0
	s_nop 0
	s_nop 0
